# inverted priority: load segments at prio 1, MMA segments at prio 0, both halves (4 main GEMM loops)
# baseline (speedup 1.0000x reference)
; #define WAIT_V(n) asm volatile("s_waitcnt vmcnt(" #n ")" ::: "memory")
; #define WAIT_L(n) asm volatile("s_waitcnt lgkmcnt(" #n ")" ::: "memory")
; #define BAR __builtin_amdgcn_s_barrier()
; #define SCHED __builtin_amdgcn_sched_barrier(0)
; #define STG_A(b, h, ptr) do { const char* _g = (ptr) + (h) * ahalf; LAS unsigned char* _l = lw + ((b) * 2 + (h)) * 16384; GLDS(_g + voa0, _l); GLDS(_g + voa1, _l + 8192); } while (0)
; #define STG_B(b, h, ptr) do { const char* _g = (ptr) + (h) * bhalf; LAS unsigned char* _l = lw + 65536 + ((b) * 2 + (h)) * 16384; GLDS(_g + vob0, _l); GLDS(_g + vob1, _l + 8192); } while (0)
; #define LDA(dst, b, h) _Pragma("unroll") for (int m = 0; m < 4; ++m) _Pragma("unroll") for (int k = 0; k < 2; ++k) dst[m][k] = *(const LAS bf16x8*)(la + ((b) * 2 + (h)) * 16384 + m * 2048 + k * 1024)
; #define LDB(dst, b, h) _Pragma("unroll") for (int n = 0; n < 2; ++n) _Pragma("unroll") for (int k = 0; k < 2; ++k) dst[n][k] = *(const LAS bf16x8*)(lb + ((b) * 2 + (h)) * 16384 + n * 2048 + k * 1024)
; template <int BMODE, class Epi, class TileFn>
; DEV void gemm_loop(LAS unsigned char* lds, const bf16_t* __restrict__ A, int lda, const bf16_t* __restrict__ B, int ldb, int K, const Epi& epi, int t0, int tstep, int tend, const TileFn& tf) {
;     ...
;     for (int tt = t0;; tt += tstep, par ^= 1) {
;         const bool has_next = tt + tstep < tend;
;         epi.prefetch(lds, brow, par, tid);
;         int nrow = brow, ncol = bcol;
;         if (has_next) tf(tt + tstep, nrow, ncol);
;         const char* nA = (const char*)(A + (size_t)nrow * lda);
;         const char* nB = BMODE == 0 ? (const char*)(B + (size_t)ncol * ldb) : (const char*)(B + (size_t)ncol * 8);
;         for (int t = 0; t < nt; t += 2) {
;             const bool last = (t == nt - 2);
;             const char* a1 = cA + (size_t)(t + 1) * 128;
;             const char* a2 = last ? nA : cA + (size_t)(t + 2) * 128;
;             const char* b2 = last ? nB : cB + (size_t)(t + 2) * bks;
;             const char* a3 = a2 + 128; const char* b3 = b2 + bks;
;             LDB(B0, 0, 0); LDB(B1, 0, 1); SCHED; LDA(At, 0, 0); STG_A(1, 1, a1);
;             WAIT_V(8); WAIT_L(0); BAR; MMA(0, 0, At, B0); MMA(0, 1, At, B1); BAR; SCHED;
;             LDA(At, 0, 1); STG_B(0, 0, b2); STG_B(0, 1, b2); STG_A(0, 0, a2);
;             WAIT_V(8); WAIT_L(0); BAR; MMA(1, 0, At, B0); MMA(1, 1, At, B1); BAR; SCHED;
.LBB0_440:
	s_ashr_i32 s53, s52, 31
	s_lshl_b64 s[76:77], s[52:53], 11
	s_add_u32 s29, s72, s76
	s_addc_u32 s30, s73, s77
	s_ashr_i32 s55, s54, 31
	s_lshl_b64 s[80:81], s[54:55], 11
	s_add_u32 s50, s46, s80
	s_addc_u32 s53, s47, s81
	s_add_u32 s55, s66, s36
	s_addc_u32 s74, s67, s37
	v_readlane_b32 s31, v254, 51
	s_add_u32 s75, s31, s8
	v_readlane_b32 s8, v254, 52
	v_lshl_add_u64 v[140:141], v[136:137], 0, s[36:37]
	v_lshl_add_u64 v[142:143], v[138:139], 0, s[36:37]
	s_addc_u32 s83, s8, s9
	s_mov_b32 s92, -2
	s_mov_b64 s[36:37], 0
	s_setprio 1
	ds_read_b128 v[162:165], v160
	ds_read_b128 v[166:169], v160 offset:1024
	ds_read_b128 v[170:173], v160 offset:2048
	ds_read_b128 v[174:177], v160 offset:3072
	ds_read_b128 v[178:181], v160 offset:16384
	ds_read_b128 v[182:185], v160 offset:17408
	ds_read_b128 v[196:199], v160 offset:18432
	ds_read_b128 v[200:203], v160 offset:19456
	s_add_u32 s8, s55, s36
	s_addc_u32 s9, s74, s37
	s_add_u32 s8, s8, 0x62e6100
	s_addc_u32 s9, s9, 0
	s_add_u32 s31, s75, s36
	s_addc_u32 s93, s83, s37
	s_cmpk_eq_i32 s36, 0x700
	s_cselect_b32 s45, s30, s9
	s_cselect_b32 s44, s29, s8
	s_cselect_b32 s9, s53, s93
	s_cselect_b32 s8, s50, s31
	v_add_u32_e32 v194, 0xc000, v145
	v_lshl_add_u64 v[186:187], v[140:141], 0, s[36:37]
	v_readfirstlane_b32 s31, v194
	v_add_u32_e32 v194, 0xe000, v145
	s_mov_b32 m0, s31
	v_readfirstlane_b32 s31, v194
	ds_read_b128 v[212:215], v161
	ds_read_b128 v[216:219], v161 offset:1024
	ds_read_b128 v[220:223], v161 offset:2048
	ds_read_b128 v[224:227], v161 offset:3072
	ds_read_b128 v[228:231], v161 offset:4096
	ds_read_b128 v[232:235], v161 offset:5120
	ds_read_b128 v[236:239], v161 offset:6144
	ds_read_b128 v[240:243], v161 offset:7168
	global_load_lds_dwordx4 v[186:187], off
	v_lshl_add_u64 v[186:187], v[142:143], 0, s[36:37]
	s_mov_b32 m0, s31
	s_nop 0
	global_load_lds_dwordx4 v[186:187], off
	s_waitcnt vmcnt(8)
	s_waitcnt lgkmcnt(0)
	s_barrier
	s_setprio 0
	v_mfma_f32_16x16x32_bf16 v[124:127], v[162:165], v[212:215], 0
	v_mfma_f32_16x16x32_bf16 v[120:123], v[170:173], v[212:215], 0
	v_mfma_f32_16x16x32_bf16 v[108:111], v[162:165], v[220:223], 0
	v_mfma_f32_16x16x32_bf16 v[104:107], v[170:173], v[220:223], 0
	v_mfma_f32_16x16x32_bf16 v[92:95], v[162:165], v[228:231], 0
	v_mfma_f32_16x16x32_bf16 v[88:91], v[170:173], v[228:231], 0
	v_mfma_f32_16x16x32_bf16 v[76:79], v[162:165], v[236:239], 0
	v_mfma_f32_16x16x32_bf16 v[72:75], v[170:173], v[236:239], 0
	v_mfma_f32_16x16x32_bf16 v[124:127], v[166:169], v[216:219], v[124:127]
	v_mfma_f32_16x16x32_bf16 v[120:123], v[174:177], v[216:219], v[120:123]
	v_mfma_f32_16x16x32_bf16 v[108:111], v[166:169], v[224:227], v[108:111]
	v_mfma_f32_16x16x32_bf16 v[104:107], v[174:177], v[224:227], v[104:107]
	v_mfma_f32_16x16x32_bf16 v[92:95], v[166:169], v[232:235], v[92:95]
	v_mfma_f32_16x16x32_bf16 v[88:91], v[174:177], v[232:235], v[88:91]
	v_mfma_f32_16x16x32_bf16 v[76:79], v[166:169], v[240:243], v[76:79]
	v_mfma_f32_16x16x32_bf16 v[72:75], v[174:177], v[240:243], v[72:75]
	v_mfma_f32_16x16x32_bf16 v[116:119], v[178:181], v[212:215], 0
	v_mfma_f32_16x16x32_bf16 v[112:115], v[196:199], v[212:215], 0
	v_mfma_f32_16x16x32_bf16 v[100:103], v[178:181], v[220:223], 0
	v_mfma_f32_16x16x32_bf16 v[96:99], v[196:199], v[220:223], 0
	v_mfma_f32_16x16x32_bf16 v[84:87], v[178:181], v[228:231], 0
	v_mfma_f32_16x16x32_bf16 v[80:83], v[196:199], v[228:231], 0
	v_mfma_f32_16x16x32_bf16 v[68:71], v[178:181], v[236:239], 0
	v_mfma_f32_16x16x32_bf16 v[64:67], v[196:199], v[236:239], 0
	v_mfma_f32_16x16x32_bf16 v[116:119], v[182:185], v[216:219], v[116:119]
	v_mfma_f32_16x16x32_bf16 v[112:115], v[200:203], v[216:219], v[112:115]
	v_mfma_f32_16x16x32_bf16 v[100:103], v[182:185], v[224:227], v[100:103]
	v_mfma_f32_16x16x32_bf16 v[96:99], v[200:203], v[224:227], v[96:99]
	v_mfma_f32_16x16x32_bf16 v[84:87], v[182:185], v[232:235], v[84:87]
	v_mfma_f32_16x16x32_bf16 v[80:83], v[200:203], v[232:235], v[80:83]
	v_mfma_f32_16x16x32_bf16 v[68:71], v[182:185], v[240:243], v[68:71]
	v_mfma_f32_16x16x32_bf16 v[64:67], v[200:203], v[240:243], v[64:67]
	s_barrier
	s_setprio 1
	v_readfirstlane_b32 s31, v146
	v_lshl_add_u64 v[186:187], s[8:9], 0, v[130:131]
	s_mov_b32 m0, s31
	v_readfirstlane_b32 s31, v147
	s_add_u32 s94, s8, 0x40000
	ds_read_b128 v[212:215], v161 offset:16384
	ds_read_b128 v[216:219], v161 offset:17408
	ds_read_b128 v[220:223], v161 offset:18432
	ds_read_b128 v[224:227], v161 offset:19456
	ds_read_b128 v[228:231], v161 offset:20480
	ds_read_b128 v[232:235], v161 offset:21504
	ds_read_b128 v[236:239], v161 offset:22528
	ds_read_b128 v[240:243], v161 offset:23552
	global_load_lds_dwordx4 v[186:187], off
	v_lshl_add_u64 v[204:205], s[8:9], 0, v[132:133]
	s_mov_b32 m0, s31
	s_addc_u32 s95, s9, 0
	v_readfirstlane_b32 s31, v148
	global_load_lds_dwordx4 v[204:205], off
	v_lshl_add_u64 v[244:245], s[94:95], 0, v[130:131]
	s_mov_b32 m0, s31
	v_readfirstlane_b32 s31, v149
	global_load_lds_dwordx4 v[244:245], off
	v_lshl_add_u64 v[244:245], s[94:95], 0, v[132:133]
	s_mov_b32 m0, s31
	v_readfirstlane_b32 s31, v145
	global_load_lds_dwordx4 v[244:245], off
	v_lshl_add_u64 v[244:245], s[44:45], 0, v[128:129]
	s_mov_b32 m0, s31
	v_readfirstlane_b32 s31, v150
	global_load_lds_dwordx4 v[244:245], off
	v_lshl_add_u64 v[246:247], s[44:45], 0, v[134:135]
	s_mov_b32 m0, s31
	s_nop 0
	global_load_lds_dwordx4 v[246:247], off
	s_waitcnt vmcnt(8)
	s_waitcnt lgkmcnt(0)
	s_barrier
; #define WAIT_V(n) asm volatile("s_waitcnt vmcnt(" #n ")" ::: "memory")
; #define WAIT_L(n) asm volatile("s_waitcnt lgkmcnt(" #n ")" ::: "memory")
; #define BAR __builtin_amdgcn_s_barrier()
; #define SCHED __builtin_amdgcn_sched_barrier(0)
; #define STG_A(b, h, ptr) do { const char* _g = (ptr) + (h) * ahalf; LAS unsigned char* _l = lw + ((b) * 2 + (h)) * 16384; GLDS(_g + voa0, _l); GLDS(_g + voa1, _l + 8192); } while (0)
; #define STG_B(b, h, ptr) do { const char* _g = (ptr) + (h) * bhalf; LAS unsigned char* _l = lw + 65536 + ((b) * 2 + (h)) * 16384; GLDS(_g + vob0, _l); GLDS(_g + vob1, _l + 8192); } while (0)
; #define LDA(dst, b, h) _Pragma("unroll") for (int m = 0; m < 4; ++m) _Pragma("unroll") for (int k = 0; k < 2; ++k) dst[m][k] = *(const LAS bf16x8*)(la + ((b) * 2 + (h)) * 16384 + m * 2048 + k * 1024)
; #define LDB(dst, b, h) _Pragma("unroll") for (int n = 0; n < 2; ++n) _Pragma("unroll") for (int k = 0; k < 2; ++k) dst[n][k] = *(const LAS bf16x8*)(lb + ((b) * 2 + (h)) * 16384 + n * 2048 + k * 1024)
; #define MMA(ai, bj, Af, Bf) do { __builtin_amdgcn_s_setprio(1); \
;     _Pragma("unroll") for (int m = 0; m < 4; ++m) _Pragma("unroll") for (int n = 0; n < 2; ++n) _Pragma("unroll") for (int k = 0; k < 2; ++k) \
;         acc[ai][bj][m][n] = __builtin_amdgcn_mfma_f32_16x16x32_bf16(Bf[n][k], Af[m][k], acc[ai][bj][m][n], 0, 0, 0); \
;     __builtin_amdgcn_s_setprio(0); } while (0)
; template <int BMODE, class Epi, class TileFn>
; DEV void gemm_loop(LAS unsigned char* lds, const bf16_t* __restrict__ A, int lda, const bf16_t* __restrict__ B, int ldb, int K, const Epi& epi, int t0, int tstep, int tend, const TileFn& tf) {
;     ...
;         for (int t = 0; t < nt; t += 2) {
;             const bool last = (t == nt - 2);
;             const char* a1 = cA + (size_t)(t + 1) * 128;
;             const char* a2 = last ? nA : cA + (size_t)(t + 2) * 128;
;             const char* b2 = last ? nB : cB + (size_t)(t + 2) * bks;
;             const char* a3 = a2 + 128; const char* b3 = b2 + bks;
;             LDB(B0, 0, 0); LDB(B1, 0, 1); SCHED; LDA(At, 0, 0); STG_A(1, 1, a1);
;             WAIT_V(8); WAIT_L(0); BAR; MMA(0, 0, At, B0); MMA(0, 1, At, B1); BAR; SCHED;
;             LDA(At, 0, 1); STG_B(0, 0, b2); STG_B(0, 1, b2); STG_A(0, 0, a2);
;             WAIT_V(8); WAIT_L(0); BAR; MMA(1, 0, At, B0); MMA(1, 1, At, B1); BAR; SCHED;
	s_setprio 0
	v_mfma_f32_16x16x32_bf16 v[60:63], v[162:165], v[212:215], 0
	v_mfma_f32_16x16x32_bf16 v[56:59], v[170:173], v[212:215], 0
	v_mfma_f32_16x16x32_bf16 v[44:47], v[162:165], v[220:223], 0
	v_mfma_f32_16x16x32_bf16 v[40:43], v[170:173], v[220:223], 0
	v_mfma_f32_16x16x32_bf16 v[28:31], v[162:165], v[228:231], 0
	v_mfma_f32_16x16x32_bf16 v[24:27], v[170:173], v[228:231], 0
	v_mfma_f32_16x16x32_bf16 v[12:15], v[162:165], v[236:239], 0
	v_mfma_f32_16x16x32_bf16 v[8:11], v[170:173], v[236:239], 0
	v_mfma_f32_16x16x32_bf16 v[60:63], v[166:169], v[216:219], v[60:63]
	v_mfma_f32_16x16x32_bf16 v[56:59], v[174:177], v[216:219], v[56:59]
	v_mfma_f32_16x16x32_bf16 v[44:47], v[166:169], v[224:227], v[44:47]
	v_mfma_f32_16x16x32_bf16 v[40:43], v[174:177], v[224:227], v[40:43]
	v_mfma_f32_16x16x32_bf16 v[28:31], v[166:169], v[232:235], v[28:31]
	v_mfma_f32_16x16x32_bf16 v[24:27], v[174:177], v[232:235], v[24:27]
	v_mfma_f32_16x16x32_bf16 v[12:15], v[166:169], v[240:243], v[12:15]
	v_mfma_f32_16x16x32_bf16 v[8:11], v[174:177], v[240:243], v[8:11]
	v_mfma_f32_16x16x32_bf16 v[52:55], v[178:181], v[212:215], 0
	v_mfma_f32_16x16x32_bf16 v[48:51], v[196:199], v[212:215], 0
	v_mfma_f32_16x16x32_bf16 v[36:39], v[178:181], v[220:223], 0
	v_mfma_f32_16x16x32_bf16 v[32:35], v[196:199], v[220:223], 0
	v_mfma_f32_16x16x32_bf16 v[20:23], v[178:181], v[228:231], 0
	v_mfma_f32_16x16x32_bf16 v[16:19], v[196:199], v[228:231], 0
	v_mfma_f32_16x16x32_bf16 v[4:7], v[178:181], v[236:239], 0
	v_mfma_f32_16x16x32_bf16 v[0:3], v[196:199], v[236:239], 0
	v_mfma_f32_16x16x32_bf16 v[52:55], v[182:185], v[216:219], v[52:55]
	v_mfma_f32_16x16x32_bf16 v[48:51], v[200:203], v[216:219], v[48:51]
	v_mfma_f32_16x16x32_bf16 v[36:39], v[182:185], v[224:227], v[36:39]
	v_mfma_f32_16x16x32_bf16 v[32:35], v[200:203], v[224:227], v[32:35]
	v_mfma_f32_16x16x32_bf16 v[20:23], v[182:185], v[232:235], v[20:23]
	v_mfma_f32_16x16x32_bf16 v[16:19], v[200:203], v[232:235], v[16:19]
	v_mfma_f32_16x16x32_bf16 v[4:7], v[182:185], v[240:243], v[4:7]
	v_mfma_f32_16x16x32_bf16 v[0:3], v[200:203], v[240:243], v[0:3]
	s_barrier
	s_setprio 1
	s_branch .Lkmid_441
.LBB0_441:
	ds_read_b128 v[162:165], v160
	ds_read_b128 v[166:169], v160 offset:1024
	ds_read_b128 v[170:173], v160 offset:2048
	ds_read_b128 v[174:177], v160 offset:3072
	ds_read_b128 v[178:181], v160 offset:16384
	ds_read_b128 v[182:185], v160 offset:17408
	ds_read_b128 v[196:199], v160 offset:18432
	ds_read_b128 v[200:203], v160 offset:19456
	s_add_u32 s8, s55, s36
	s_addc_u32 s9, s74, s37
	s_add_u32 s8, s8, 0x62e6100
	s_addc_u32 s9, s9, 0
	s_add_u32 s31, s75, s36
	s_addc_u32 s93, s83, s37
	s_cmpk_eq_i32 s36, 0x700
	s_cselect_b32 s45, s30, s9
	s_cselect_b32 s44, s29, s8
	s_cselect_b32 s9, s53, s93
	s_cselect_b32 s8, s50, s31
	v_add_u32_e32 v194, 0xc000, v145
	v_lshl_add_u64 v[186:187], v[140:141], 0, s[36:37]
	v_readfirstlane_b32 s31, v194
	v_add_u32_e32 v194, 0xe000, v145
	s_mov_b32 m0, s31
	v_readfirstlane_b32 s31, v194
	ds_read_b128 v[212:215], v161
	ds_read_b128 v[216:219], v161 offset:1024
	ds_read_b128 v[220:223], v161 offset:2048
	ds_read_b128 v[224:227], v161 offset:3072
	ds_read_b128 v[228:231], v161 offset:4096
	ds_read_b128 v[232:235], v161 offset:5120
	ds_read_b128 v[236:239], v161 offset:6144
	ds_read_b128 v[240:243], v161 offset:7168
	global_load_lds_dwordx4 v[186:187], off
	v_lshl_add_u64 v[186:187], v[142:143], 0, s[36:37]
	s_mov_b32 m0, s31
	s_nop 0
	global_load_lds_dwordx4 v[186:187], off
	s_waitcnt vmcnt(8)
	s_waitcnt lgkmcnt(0)
	s_barrier
	s_setprio 0
	v_mfma_f32_16x16x32_bf16 v[124:127], v[162:165], v[212:215], v[124:127]
	v_mfma_f32_16x16x32_bf16 v[120:123], v[170:173], v[212:215], v[120:123]
	v_mfma_f32_16x16x32_bf16 v[108:111], v[162:165], v[220:223], v[108:111]
	v_mfma_f32_16x16x32_bf16 v[104:107], v[170:173], v[220:223], v[104:107]
	v_mfma_f32_16x16x32_bf16 v[92:95], v[162:165], v[228:231], v[92:95]
	v_mfma_f32_16x16x32_bf16 v[88:91], v[170:173], v[228:231], v[88:91]
	v_mfma_f32_16x16x32_bf16 v[76:79], v[162:165], v[236:239], v[76:79]
	v_mfma_f32_16x16x32_bf16 v[72:75], v[170:173], v[236:239], v[72:75]
	v_mfma_f32_16x16x32_bf16 v[124:127], v[166:169], v[216:219], v[124:127]
	v_mfma_f32_16x16x32_bf16 v[120:123], v[174:177], v[216:219], v[120:123]
	v_mfma_f32_16x16x32_bf16 v[108:111], v[166:169], v[224:227], v[108:111]
	v_mfma_f32_16x16x32_bf16 v[104:107], v[174:177], v[224:227], v[104:107]
	v_mfma_f32_16x16x32_bf16 v[92:95], v[166:169], v[232:235], v[92:95]
	v_mfma_f32_16x16x32_bf16 v[88:91], v[174:177], v[232:235], v[88:91]
	v_mfma_f32_16x16x32_bf16 v[76:79], v[166:169], v[240:243], v[76:79]
	v_mfma_f32_16x16x32_bf16 v[72:75], v[174:177], v[240:243], v[72:75]
	v_mfma_f32_16x16x32_bf16 v[116:119], v[178:181], v[212:215], v[116:119]
	v_mfma_f32_16x16x32_bf16 v[112:115], v[196:199], v[212:215], v[112:115]
	v_mfma_f32_16x16x32_bf16 v[100:103], v[178:181], v[220:223], v[100:103]
	v_mfma_f32_16x16x32_bf16 v[96:99], v[196:199], v[220:223], v[96:99]
	v_mfma_f32_16x16x32_bf16 v[84:87], v[178:181], v[228:231], v[84:87]
	v_mfma_f32_16x16x32_bf16 v[80:83], v[196:199], v[228:231], v[80:83]
	v_mfma_f32_16x16x32_bf16 v[68:71], v[178:181], v[236:239], v[68:71]
	v_mfma_f32_16x16x32_bf16 v[64:67], v[196:199], v[236:239], v[64:67]
	v_mfma_f32_16x16x32_bf16 v[116:119], v[182:185], v[216:219], v[116:119]
	v_mfma_f32_16x16x32_bf16 v[112:115], v[200:203], v[216:219], v[112:115]
	v_mfma_f32_16x16x32_bf16 v[100:103], v[182:185], v[224:227], v[100:103]
	v_mfma_f32_16x16x32_bf16 v[96:99], v[200:203], v[224:227], v[96:99]
	v_mfma_f32_16x16x32_bf16 v[84:87], v[182:185], v[232:235], v[84:87]
	v_mfma_f32_16x16x32_bf16 v[80:83], v[200:203], v[232:235], v[80:83]
	v_mfma_f32_16x16x32_bf16 v[68:71], v[182:185], v[240:243], v[68:71]
	v_mfma_f32_16x16x32_bf16 v[64:67], v[200:203], v[240:243], v[64:67]
	s_barrier
; #define WAIT_V(n) asm volatile("s_waitcnt vmcnt(" #n ")" ::: "memory")
; #define WAIT_L(n) asm volatile("s_waitcnt lgkmcnt(" #n ")" ::: "memory")
; #define BAR __builtin_amdgcn_s_barrier()
; #define SCHED __builtin_amdgcn_sched_barrier(0)
; #define STG_A(b, h, ptr) do { const char* _g = (ptr) + (h) * ahalf; LAS unsigned char* _l = lw + ((b) * 2 + (h)) * 16384; GLDS(_g + voa0, _l); GLDS(_g + voa1, _l + 8192); } while (0)
; #define STG_B(b, h, ptr) do { const char* _g = (ptr) + (h) * bhalf; LAS unsigned char* _l = lw + 65536 + ((b) * 2 + (h)) * 16384; GLDS(_g + vob0, _l); GLDS(_g + vob1, _l + 8192); } while (0)
; #define LDA(dst, b, h) _Pragma("unroll") for (int m = 0; m < 4; ++m) _Pragma("unroll") for (int k = 0; k < 2; ++k) dst[m][k] = *(const LAS bf16x8*)(la + ((b) * 2 + (h)) * 16384 + m * 2048 + k * 1024)
; #define LDB(dst, b, h) _Pragma("unroll") for (int n = 0; n < 2; ++n) _Pragma("unroll") for (int k = 0; k < 2; ++k) dst[n][k] = *(const LAS bf16x8*)(lb + ((b) * 2 + (h)) * 16384 + n * 2048 + k * 1024)
; #define MMA(ai, bj, Af, Bf) do { __builtin_amdgcn_s_setprio(1); \
;     _Pragma("unroll") for (int m = 0; m < 4; ++m) _Pragma("unroll") for (int n = 0; n < 2; ++n) _Pragma("unroll") for (int k = 0; k < 2; ++k) \
;         acc[ai][bj][m][n] = __builtin_amdgcn_mfma_f32_16x16x32_bf16(Bf[n][k], Af[m][k], acc[ai][bj][m][n], 0, 0, 0); \
;     __builtin_amdgcn_s_setprio(0); } while (0)
; template <int BMODE, class Epi, class TileFn>
; DEV void gemm_loop(LAS unsigned char* lds, const bf16_t* __restrict__ A, int lda, const bf16_t* __restrict__ B, int ldb, int K, const Epi& epi, int t0, int tstep, int tend, const TileFn& tf) {
;     ...
;             LDA(At, 0, 1); STG_B(0, 0, b2); STG_B(0, 1, b2); STG_A(0, 0, a2);
;             WAIT_V(8); WAIT_L(0); BAR; MMA(1, 0, At, B0); MMA(1, 1, At, B1); BAR; SCHED;
;             LDB(B0, 1, 0); LDB(B1, 1, 1); SCHED; LDA(At, 1, 0); STG_A(0, 1, a2);
;             WAIT_V(8); WAIT_L(0); BAR; MMA(0, 0, At, B0); MMA(0, 1, At, B1); BAR; SCHED;
	s_setprio 1
	v_readfirstlane_b32 s31, v146
	v_lshl_add_u64 v[186:187], s[8:9], 0, v[130:131]
	s_mov_b32 m0, s31
	v_readfirstlane_b32 s31, v147
	s_add_u32 s94, s8, 0x40000
	ds_read_b128 v[212:215], v161 offset:16384
	ds_read_b128 v[216:219], v161 offset:17408
	ds_read_b128 v[220:223], v161 offset:18432
	ds_read_b128 v[224:227], v161 offset:19456
	ds_read_b128 v[228:231], v161 offset:20480
	ds_read_b128 v[232:235], v161 offset:21504
	ds_read_b128 v[236:239], v161 offset:22528
	ds_read_b128 v[240:243], v161 offset:23552
	global_load_lds_dwordx4 v[186:187], off
	v_lshl_add_u64 v[204:205], s[8:9], 0, v[132:133]
	s_mov_b32 m0, s31
	s_addc_u32 s95, s9, 0
	v_readfirstlane_b32 s31, v148
	global_load_lds_dwordx4 v[204:205], off
	v_lshl_add_u64 v[244:245], s[94:95], 0, v[130:131]
	s_mov_b32 m0, s31
	v_readfirstlane_b32 s31, v149
	global_load_lds_dwordx4 v[244:245], off
	v_lshl_add_u64 v[244:245], s[94:95], 0, v[132:133]
	s_mov_b32 m0, s31
	v_readfirstlane_b32 s31, v145
	global_load_lds_dwordx4 v[244:245], off
	v_lshl_add_u64 v[244:245], s[44:45], 0, v[128:129]
	s_mov_b32 m0, s31
	v_readfirstlane_b32 s31, v150
	global_load_lds_dwordx4 v[244:245], off
	v_lshl_add_u64 v[246:247], s[44:45], 0, v[134:135]
	s_mov_b32 m0, s31
	s_nop 0
	global_load_lds_dwordx4 v[246:247], off
	s_waitcnt vmcnt(8)
	s_waitcnt lgkmcnt(0)
	s_barrier
	s_setprio 0
	v_mfma_f32_16x16x32_bf16 v[60:63], v[162:165], v[212:215], v[60:63]
	v_mfma_f32_16x16x32_bf16 v[56:59], v[170:173], v[212:215], v[56:59]
	v_mfma_f32_16x16x32_bf16 v[44:47], v[162:165], v[220:223], v[44:47]
	v_mfma_f32_16x16x32_bf16 v[40:43], v[170:173], v[220:223], v[40:43]
	v_mfma_f32_16x16x32_bf16 v[28:31], v[162:165], v[228:231], v[28:31]
	v_mfma_f32_16x16x32_bf16 v[24:27], v[170:173], v[228:231], v[24:27]
	v_mfma_f32_16x16x32_bf16 v[12:15], v[162:165], v[236:239], v[12:15]
	v_mfma_f32_16x16x32_bf16 v[8:11], v[170:173], v[236:239], v[8:11]
	v_mfma_f32_16x16x32_bf16 v[60:63], v[166:169], v[216:219], v[60:63]
	v_mfma_f32_16x16x32_bf16 v[56:59], v[174:177], v[216:219], v[56:59]
	v_mfma_f32_16x16x32_bf16 v[44:47], v[166:169], v[224:227], v[44:47]
	v_mfma_f32_16x16x32_bf16 v[40:43], v[174:177], v[224:227], v[40:43]
	v_mfma_f32_16x16x32_bf16 v[28:31], v[166:169], v[232:235], v[28:31]
	v_mfma_f32_16x16x32_bf16 v[24:27], v[174:177], v[232:235], v[24:27]
	v_mfma_f32_16x16x32_bf16 v[12:15], v[166:169], v[240:243], v[12:15]
	v_mfma_f32_16x16x32_bf16 v[8:11], v[174:177], v[240:243], v[8:11]
	v_mfma_f32_16x16x32_bf16 v[52:55], v[178:181], v[212:215], v[52:55]
	v_mfma_f32_16x16x32_bf16 v[48:51], v[196:199], v[212:215], v[48:51]
	v_mfma_f32_16x16x32_bf16 v[36:39], v[178:181], v[220:223], v[36:39]
	v_mfma_f32_16x16x32_bf16 v[32:35], v[196:199], v[220:223], v[32:35]
	v_mfma_f32_16x16x32_bf16 v[20:23], v[178:181], v[228:231], v[20:23]
	v_mfma_f32_16x16x32_bf16 v[16:19], v[196:199], v[228:231], v[16:19]
	v_mfma_f32_16x16x32_bf16 v[4:7], v[178:181], v[236:239], v[4:7]
	v_mfma_f32_16x16x32_bf16 v[0:3], v[196:199], v[236:239], v[0:3]
	v_mfma_f32_16x16x32_bf16 v[52:55], v[182:185], v[216:219], v[52:55]
	v_mfma_f32_16x16x32_bf16 v[48:51], v[200:203], v[216:219], v[48:51]
	v_mfma_f32_16x16x32_bf16 v[36:39], v[182:185], v[224:227], v[36:39]
	v_mfma_f32_16x16x32_bf16 v[32:35], v[200:203], v[224:227], v[32:35]
	v_mfma_f32_16x16x32_bf16 v[20:23], v[182:185], v[232:235], v[20:23]
	v_mfma_f32_16x16x32_bf16 v[16:19], v[200:203], v[232:235], v[16:19]
	v_mfma_f32_16x16x32_bf16 v[4:7], v[182:185], v[240:243], v[4:7]
	v_mfma_f32_16x16x32_bf16 v[0:3], v[200:203], v[240:243], v[0:3]
	s_barrier
	s_setprio 1
.Lkmid_441:
	ds_read_b128 v[162:165], v160 offset:32768
	ds_read_b128 v[166:169], v160 offset:33792
	ds_read_b128 v[170:173], v160 offset:34816
	ds_read_b128 v[174:177], v160 offset:35840
	ds_read_b128 v[178:181], v160 offset:49152
	ds_read_b128 v[182:185], v160 offset:50176
	ds_read_b128 v[196:199], v160 offset:51200
	ds_read_b128 v[200:203], v160 offset:52224
	s_add_u32 s44, s44, 0x40000
	s_addc_u32 s45, s45, 0
	v_readfirstlane_b32 s31, v151
	v_lshl_add_u64 v[248:249], s[44:45], 0, v[128:129]
	s_mov_b32 m0, s31
	v_readfirstlane_b32 s31, v152
	ds_read_b128 v[212:215], v161 offset:32768
	ds_read_b128 v[216:219], v161 offset:33792
	ds_read_b128 v[220:223], v161 offset:34816
	ds_read_b128 v[224:227], v161 offset:35840
	ds_read_b128 v[228:231], v161 offset:36864
	ds_read_b128 v[232:235], v161 offset:37888
	ds_read_b128 v[236:239], v161 offset:38912
	ds_read_b128 v[240:243], v161 offset:39936
	global_load_lds_dwordx4 v[248:249], off
	v_lshl_add_u64 v[248:249], s[44:45], 0, v[134:135]
	s_mov_b32 m0, s31
	s_nop 0
	global_load_lds_dwordx4 v[248:249], off
	s_waitcnt vmcnt(8)
	s_waitcnt lgkmcnt(0)
	s_barrier
; #define WAIT_V(n) asm volatile("s_waitcnt vmcnt(" #n ")" ::: "memory")
; #define WAIT_L(n) asm volatile("s_waitcnt lgkmcnt(" #n ")" ::: "memory")
; #define BAR __builtin_amdgcn_s_barrier()
; #define SCHED __builtin_amdgcn_sched_barrier(0)
; #define STG_A(b, h, ptr) do { const char* _g = (ptr) + (h) * ahalf; LAS unsigned char* _l = lw + ((b) * 2 + (h)) * 16384; GLDS(_g + voa0, _l); GLDS(_g + voa1, _l + 8192); } while (0)
; #define STG_B(b, h, ptr) do { const char* _g = (ptr) + (h) * bhalf; LAS unsigned char* _l = lw + 65536 + ((b) * 2 + (h)) * 16384; GLDS(_g + vob0, _l); GLDS(_g + vob1, _l + 8192); } while (0)
; #define LDA(dst, b, h) _Pragma("unroll") for (int m = 0; m < 4; ++m) _Pragma("unroll") for (int k = 0; k < 2; ++k) dst[m][k] = *(const LAS bf16x8*)(la + ((b) * 2 + (h)) * 16384 + m * 2048 + k * 1024)
; #define MMA(ai, bj, Af, Bf) do { __builtin_amdgcn_s_setprio(1); \
;     _Pragma("unroll") for (int m = 0; m < 4; ++m) _Pragma("unroll") for (int n = 0; n < 2; ++n) _Pragma("unroll") for (int k = 0; k < 2; ++k) \
;         acc[ai][bj][m][n] = __builtin_amdgcn_mfma_f32_16x16x32_bf16(Bf[n][k], Af[m][k], acc[ai][bj][m][n], 0, 0, 0); \
;     __builtin_amdgcn_s_setprio(0); } while (0)
; template <int BMODE, class Epi, class TileFn>
; DEV void gemm_loop(LAS unsigned char* lds, const bf16_t* __restrict__ A, int lda, const bf16_t* __restrict__ B, int ldb, int K, const Epi& epi, int t0, int tstep, int tend, const TileFn& tf) {
;     ...
;             WAIT_V(8); WAIT_L(0); BAR; MMA(0, 0, At, B0); MMA(0, 1, At, B1); BAR; SCHED;
;             LDA(At, 1, 1); STG_B(1, 0, b3); STG_B(1, 1, b3); STG_A(1, 0, a3);
;             WAIT_V(8); WAIT_L(0); BAR; MMA(1, 0, At, B0); MMA(1, 1, At, B1); BAR; SCHED;
;         }
	s_setprio 0
	v_mfma_f32_16x16x32_bf16 v[124:127], v[162:165], v[212:215], v[124:127]
	v_mfma_f32_16x16x32_bf16 v[120:123], v[170:173], v[212:215], v[120:123]
	v_mfma_f32_16x16x32_bf16 v[108:111], v[162:165], v[220:223], v[108:111]
	v_mfma_f32_16x16x32_bf16 v[104:107], v[170:173], v[220:223], v[104:107]
	v_mfma_f32_16x16x32_bf16 v[92:95], v[162:165], v[228:231], v[92:95]
	v_mfma_f32_16x16x32_bf16 v[88:91], v[170:173], v[228:231], v[88:91]
	v_mfma_f32_16x16x32_bf16 v[76:79], v[162:165], v[236:239], v[76:79]
	v_mfma_f32_16x16x32_bf16 v[72:75], v[170:173], v[236:239], v[72:75]
	v_mfma_f32_16x16x32_bf16 v[124:127], v[166:169], v[216:219], v[124:127]
	v_mfma_f32_16x16x32_bf16 v[120:123], v[174:177], v[216:219], v[120:123]
	v_mfma_f32_16x16x32_bf16 v[108:111], v[166:169], v[224:227], v[108:111]
	v_mfma_f32_16x16x32_bf16 v[104:107], v[174:177], v[224:227], v[104:107]
	v_mfma_f32_16x16x32_bf16 v[92:95], v[166:169], v[232:235], v[92:95]
	v_mfma_f32_16x16x32_bf16 v[88:91], v[174:177], v[232:235], v[88:91]
	v_mfma_f32_16x16x32_bf16 v[76:79], v[166:169], v[240:243], v[76:79]
	v_mfma_f32_16x16x32_bf16 v[72:75], v[174:177], v[240:243], v[72:75]
	v_mfma_f32_16x16x32_bf16 v[116:119], v[178:181], v[212:215], v[116:119]
	v_mfma_f32_16x16x32_bf16 v[112:115], v[196:199], v[212:215], v[112:115]
	v_mfma_f32_16x16x32_bf16 v[100:103], v[178:181], v[220:223], v[100:103]
	v_mfma_f32_16x16x32_bf16 v[96:99], v[196:199], v[220:223], v[96:99]
	v_mfma_f32_16x16x32_bf16 v[84:87], v[178:181], v[228:231], v[84:87]
	v_mfma_f32_16x16x32_bf16 v[80:83], v[196:199], v[228:231], v[80:83]
	v_mfma_f32_16x16x32_bf16 v[68:71], v[178:181], v[236:239], v[68:71]
	v_mfma_f32_16x16x32_bf16 v[64:67], v[196:199], v[236:239], v[64:67]
	v_mfma_f32_16x16x32_bf16 v[116:119], v[182:185], v[216:219], v[116:119]
	v_mfma_f32_16x16x32_bf16 v[112:115], v[200:203], v[216:219], v[112:115]
	v_mfma_f32_16x16x32_bf16 v[100:103], v[182:185], v[224:227], v[100:103]
	v_mfma_f32_16x16x32_bf16 v[96:99], v[200:203], v[224:227], v[96:99]
	v_mfma_f32_16x16x32_bf16 v[84:87], v[182:185], v[232:235], v[84:87]
	v_mfma_f32_16x16x32_bf16 v[80:83], v[200:203], v[232:235], v[80:83]
	v_mfma_f32_16x16x32_bf16 v[68:71], v[182:185], v[240:243], v[68:71]
	v_mfma_f32_16x16x32_bf16 v[64:67], v[200:203], v[240:243], v[64:67]
	s_barrier
	s_setprio 1
	v_readfirstlane_b32 s31, v153
	v_lshl_add_u64 v[186:187], v[186:187], 0, s[2:3]
	s_mov_b32 m0, s31
	v_readfirstlane_b32 s31, v154
	s_add_u32 s8, s8, 0x40080
	ds_read_b128 v[212:215], v161 offset:49152
	ds_read_b128 v[216:219], v161 offset:50176
	ds_read_b128 v[220:223], v161 offset:51200
	ds_read_b128 v[224:227], v161 offset:52224
	ds_read_b128 v[228:231], v161 offset:53248
	ds_read_b128 v[232:235], v161 offset:54272
	ds_read_b128 v[236:239], v161 offset:55296
	ds_read_b128 v[240:243], v161 offset:56320
	global_load_lds_dwordx4 v[186:187], off
	v_lshl_add_u64 v[186:187], v[204:205], 0, s[2:3]
	s_mov_b32 m0, s31
	s_addc_u32 s9, s9, 0
	v_readfirstlane_b32 s31, v157
	global_load_lds_dwordx4 v[186:187], off
	v_lshl_add_u64 v[186:187], s[8:9], 0, v[130:131]
	s_mov_b32 m0, s31
	s_nop 0
	global_load_lds_dwordx4 v[186:187], off
	v_lshl_add_u64 v[186:187], s[8:9], 0, v[132:133]
	v_readfirstlane_b32 s8, v158
	s_mov_b32 m0, s8
	v_readfirstlane_b32 s8, v155
	global_load_lds_dwordx4 v[186:187], off
	v_lshl_add_u64 v[186:187], v[244:245], 0, s[2:3]
	s_mov_b32 m0, s8
	v_readfirstlane_b32 s8, v156
	global_load_lds_dwordx4 v[186:187], off
	v_lshl_add_u64 v[186:187], v[246:247], 0, s[2:3]
	s_mov_b32 m0, s8
	s_nop 0
	global_load_lds_dwordx4 v[186:187], off
	s_waitcnt vmcnt(8)
	s_waitcnt lgkmcnt(0)
	s_barrier
	s_setprio 0
	v_mfma_f32_16x16x32_bf16 v[60:63], v[162:165], v[212:215], v[60:63]
	v_mfma_f32_16x16x32_bf16 v[56:59], v[170:173], v[212:215], v[56:59]
	v_mfma_f32_16x16x32_bf16 v[44:47], v[162:165], v[220:223], v[44:47]
	v_mfma_f32_16x16x32_bf16 v[40:43], v[170:173], v[220:223], v[40:43]
	v_mfma_f32_16x16x32_bf16 v[28:31], v[162:165], v[228:231], v[28:31]
	v_mfma_f32_16x16x32_bf16 v[24:27], v[170:173], v[228:231], v[24:27]
	v_mfma_f32_16x16x32_bf16 v[12:15], v[162:165], v[236:239], v[12:15]
	v_mfma_f32_16x16x32_bf16 v[8:11], v[170:173], v[236:239], v[8:11]
	v_mfma_f32_16x16x32_bf16 v[60:63], v[166:169], v[216:219], v[60:63]
	v_mfma_f32_16x16x32_bf16 v[56:59], v[174:177], v[216:219], v[56:59]
	v_mfma_f32_16x16x32_bf16 v[44:47], v[166:169], v[224:227], v[44:47]
	v_mfma_f32_16x16x32_bf16 v[40:43], v[174:177], v[224:227], v[40:43]
	v_mfma_f32_16x16x32_bf16 v[28:31], v[166:169], v[232:235], v[28:31]
	v_mfma_f32_16x16x32_bf16 v[24:27], v[174:177], v[232:235], v[24:27]
	v_mfma_f32_16x16x32_bf16 v[12:15], v[166:169], v[240:243], v[12:15]
	v_mfma_f32_16x16x32_bf16 v[8:11], v[174:177], v[240:243], v[8:11]
	v_mfma_f32_16x16x32_bf16 v[52:55], v[178:181], v[212:215], v[52:55]
	v_mfma_f32_16x16x32_bf16 v[48:51], v[196:199], v[212:215], v[48:51]
	v_mfma_f32_16x16x32_bf16 v[36:39], v[178:181], v[220:223], v[36:39]
	v_mfma_f32_16x16x32_bf16 v[32:35], v[196:199], v[220:223], v[32:35]
	v_mfma_f32_16x16x32_bf16 v[20:23], v[178:181], v[228:231], v[20:23]
	v_mfma_f32_16x16x32_bf16 v[16:19], v[196:199], v[228:231], v[16:19]
	v_mfma_f32_16x16x32_bf16 v[4:7], v[178:181], v[236:239], v[4:7]
	v_mfma_f32_16x16x32_bf16 v[0:3], v[196:199], v[236:239], v[0:3]
	v_mfma_f32_16x16x32_bf16 v[52:55], v[182:185], v[216:219], v[52:55]
	v_mfma_f32_16x16x32_bf16 v[48:51], v[200:203], v[216:219], v[48:51]
	v_mfma_f32_16x16x32_bf16 v[36:39], v[182:185], v[224:227], v[36:39]
	v_mfma_f32_16x16x32_bf16 v[32:35], v[200:203], v[224:227], v[32:35]
	v_mfma_f32_16x16x32_bf16 v[20:23], v[182:185], v[232:235], v[20:23]
	v_mfma_f32_16x16x32_bf16 v[16:19], v[200:203], v[232:235], v[16:19]
	v_mfma_f32_16x16x32_bf16 v[4:7], v[182:185], v[240:243], v[4:7]
	v_mfma_f32_16x16x32_bf16 v[0:3], v[200:203], v[240:243], v[0:3]
	s_barrier
	s_setprio 1
	s_add_i32 s92, s92, 2
	s_add_u32 s36, s36, 0x100
	s_addc_u32 s37, s37, 0
	s_cmp_gt_u32 s92, 13
	s_cbranch_scc0 .LBB0_441
	s_setprio 0
	s_and_saveexec_b64 s[8:9], s[42:43]
	s_cbranch_execz .LBB0_444
	s_barrier

; #define WAIT_V(n) asm volatile("s_waitcnt vmcnt(" #n ")" ::: "memory")
; #define WAIT_L(n) asm volatile("s_waitcnt lgkmcnt(" #n ")" ::: "memory")
; #define BAR __builtin_amdgcn_s_barrier()
; #define SCHED __builtin_amdgcn_sched_barrier(0)
; #define STG_A(b, h, ptr) do { const char* _g = (ptr) + (h) * ahalf; LAS unsigned char* _l = lw + ((b) * 2 + (h)) * 16384; GLDS(_g + voa0, _l); GLDS(_g + voa1, _l + 8192); } while (0)
; #define STG_B(b, h, ptr) do { const char* _g = (ptr) + (h) * bhalf; LAS unsigned char* _l = lw + 65536 + ((b) * 2 + (h)) * 16384; GLDS(_g + vob0, _l); GLDS(_g + vob1, _l + 8192); } while (0)
; #define LDA(dst, b, h) _Pragma("unroll") for (int m = 0; m < 4; ++m) _Pragma("unroll") for (int k = 0; k < 2; ++k) dst[m][k] = *(const LAS bf16x8*)(la + ((b) * 2 + (h)) * 16384 + m * 2048 + k * 1024)
; #define LDB(dst, b, h) _Pragma("unroll") for (int n = 0; n < 2; ++n) _Pragma("unroll") for (int k = 0; k < 2; ++k) dst[n][k] = *(const LAS bf16x8*)(lb + ((b) * 2 + (h)) * 16384 + n * 2048 + k * 1024)
; template <int BMODE, class Epi, class TileFn>
; DEV void gemm_loop(LAS unsigned char* lds, const bf16_t* __restrict__ A, int lda, const bf16_t* __restrict__ B, int ldb, int K, const Epi& epi, int t0, int tstep, int tend, const TileFn& tf) {
;     ...
;     for (int tt = t0;; tt += tstep, par ^= 1) {
;         const bool has_next = tt + tstep < tend;
;         epi.prefetch(lds, brow, par, tid);
;         int nrow = brow, ncol = bcol;
;         if (has_next) tf(tt + tstep, nrow, ncol);
;         const char* nA = (const char*)(A + (size_t)nrow * lda);
;         const char* nB = BMODE == 0 ? (const char*)(B + (size_t)ncol * ldb) : (const char*)(B + (size_t)ncol * 8);
;         for (int t = 0; t < nt; t += 2) {
;             const bool last = (t == nt - 2);
;             const char* a1 = cA + (size_t)(t + 1) * 128;
;             const char* a2 = last ? nA : cA + (size_t)(t + 2) * 128;
;             const char* b2 = last ? nB : cB + (size_t)(t + 2) * bks;
;             const char* a3 = a2 + 128; const char* b3 = b2 + bks;
;             LDB(B0, 0, 0); LDB(B1, 0, 1); SCHED; LDA(At, 0, 0); STG_A(1, 1, a1);
;             WAIT_V(8); WAIT_L(0); BAR; MMA(0, 0, At, B0); MMA(0, 1, At, B1); BAR; SCHED;
;             LDA(At, 0, 1); STG_B(0, 0, b2); STG_B(0, 1, b2); STG_A(0, 0, a2);
;             WAIT_V(8); WAIT_L(0); BAR; MMA(1, 0, At, B0); MMA(1, 1, At, B1); BAR; SCHED;
.LBB0_1238:
	s_ashr_i32 s49, s48, 31
	s_lshl_b64 s[54:55], s[48:49], 11
	s_add_u32 s28, s88, s54
	s_addc_u32 s29, s89, s55
	s_ashr_i32 s53, s52, 31
	s_lshl_b64 s[74:75], s[52:53], 11
	s_add_u32 s30, s38, s74
	s_addc_u32 s37, s39, s75
	s_add_u32 s49, s66, s8
	s_addc_u32 s50, s67, s9
	v_lshl_add_u64 v[120:121], v[200:201], 0, s[8:9]
	v_lshl_add_u64 v[122:123], v[202:203], 0, s[8:9]
	v_readlane_b32 s8, v254, 61
	s_add_u32 s53, s8, s0
	v_readlane_b32 s0, v254, 62
	s_addc_u32 s80, s0, s1
	s_mov_b32 s81, -2
	s_mov_b64 s[0:1], 0
	s_setprio 1
	ds_read_b128 v[132:135], v225
	ds_read_b128 v[136:139], v225 offset:1024
	ds_read_b128 v[140:143], v225 offset:2048
	ds_read_b128 v[144:147], v225 offset:3072
	ds_read_b128 v[148:151], v225 offset:16384
	ds_read_b128 v[152:155], v225 offset:17408
	ds_read_b128 v[156:159], v225 offset:18432
	ds_read_b128 v[160:163], v225 offset:19456
	s_add_u32 s8, s49, s0
	s_addc_u32 s9, s50, s1
	s_add_u32 s8, s8, 0x18466100
	s_addc_u32 s9, s9, 0
	s_add_u32 s31, s53, s0
	s_addc_u32 s82, s80, s1
	s_cmpk_eq_i32 s0, 0x700
	s_cselect_b32 s77, s29, s9
	s_cselect_b32 s76, s28, s8
	s_cselect_b32 s9, s37, s82
	s_cselect_b32 s8, s30, s31
	v_add_u32_e32 v194, 0xc000, v211
	v_lshl_add_u64 v[204:205], v[120:121], 0, s[0:1]
	v_readfirstlane_b32 s31, v194
	v_add_u32_e32 v194, 0xe000, v211
	s_mov_b32 m0, s31
	v_readfirstlane_b32 s31, v194
	ds_read_b128 v[164:167], v226
	ds_read_b128 v[168:171], v226 offset:1024
	ds_read_b128 v[172:175], v226 offset:2048
	ds_read_b128 v[176:179], v226 offset:3072
	ds_read_b128 v[180:183], v226 offset:4096
	ds_read_b128 v[228:231], v226 offset:5120
	ds_read_b128 v[232:235], v226 offset:6144
	ds_read_b128 v[236:239], v226 offset:7168
	global_load_lds_dwordx4 v[204:205], off
	v_lshl_add_u64 v[204:205], v[122:123], 0, s[0:1]
	s_mov_b32 m0, s31
	s_nop 0
	global_load_lds_dwordx4 v[204:205], off
	s_waitcnt vmcnt(8)
	s_waitcnt lgkmcnt(0)
	s_barrier
	s_setprio 0
	v_mfma_f32_16x16x32_bf16 v[128:131], v[132:135], v[164:167], 0
	v_mfma_f32_16x16x32_bf16 v[124:127], v[140:143], v[164:167], 0
	v_mfma_f32_16x16x32_bf16 v[108:111], v[132:135], v[172:175], 0
	v_mfma_f32_16x16x32_bf16 v[104:107], v[140:143], v[172:175], 0
	v_mfma_f32_16x16x32_bf16 v[92:95], v[132:135], v[180:183], 0
	v_mfma_f32_16x16x32_bf16 v[88:91], v[140:143], v[180:183], 0
	v_mfma_f32_16x16x32_bf16 v[76:79], v[132:135], v[232:235], 0
	v_mfma_f32_16x16x32_bf16 v[72:75], v[140:143], v[232:235], 0
	v_mfma_f32_16x16x32_bf16 v[128:131], v[136:139], v[168:171], v[128:131]
	v_mfma_f32_16x16x32_bf16 v[124:127], v[144:147], v[168:171], v[124:127]
	v_mfma_f32_16x16x32_bf16 v[108:111], v[136:139], v[176:179], v[108:111]
	v_mfma_f32_16x16x32_bf16 v[104:107], v[144:147], v[176:179], v[104:107]
	v_mfma_f32_16x16x32_bf16 v[92:95], v[136:139], v[228:231], v[92:95]
	v_mfma_f32_16x16x32_bf16 v[88:91], v[144:147], v[228:231], v[88:91]
	v_mfma_f32_16x16x32_bf16 v[76:79], v[136:139], v[236:239], v[76:79]
	v_mfma_f32_16x16x32_bf16 v[72:75], v[144:147], v[236:239], v[72:75]
	v_mfma_f32_16x16x32_bf16 v[116:119], v[148:151], v[164:167], 0
	v_mfma_f32_16x16x32_bf16 v[112:115], v[156:159], v[164:167], 0
	v_mfma_f32_16x16x32_bf16 v[100:103], v[148:151], v[172:175], 0
	v_mfma_f32_16x16x32_bf16 v[96:99], v[156:159], v[172:175], 0
	v_mfma_f32_16x16x32_bf16 v[84:87], v[148:151], v[180:183], 0
	v_mfma_f32_16x16x32_bf16 v[80:83], v[156:159], v[180:183], 0
	v_mfma_f32_16x16x32_bf16 v[68:71], v[148:151], v[232:235], 0
	v_mfma_f32_16x16x32_bf16 v[64:67], v[156:159], v[232:235], 0
	v_mfma_f32_16x16x32_bf16 v[116:119], v[152:155], v[168:171], v[116:119]
	v_mfma_f32_16x16x32_bf16 v[112:115], v[160:163], v[168:171], v[112:115]
	v_mfma_f32_16x16x32_bf16 v[100:103], v[152:155], v[176:179], v[100:103]
	v_mfma_f32_16x16x32_bf16 v[96:99], v[160:163], v[176:179], v[96:99]
	v_mfma_f32_16x16x32_bf16 v[84:87], v[152:155], v[228:231], v[84:87]
	v_mfma_f32_16x16x32_bf16 v[80:83], v[160:163], v[228:231], v[80:83]
	v_mfma_f32_16x16x32_bf16 v[68:71], v[152:155], v[236:239], v[68:71]
	v_mfma_f32_16x16x32_bf16 v[64:67], v[160:163], v[236:239], v[64:67]
	s_barrier
	s_setprio 1
	v_readfirstlane_b32 s31, v212
	v_lshl_add_u64 v[204:205], s[8:9], 0, v[196:197]
	s_mov_b32 m0, s31
	v_readfirstlane_b32 s31, v213
	s_add_u32 s82, s8, 0x40000
	ds_read_b128 v[164:167], v226 offset:16384
	ds_read_b128 v[168:171], v226 offset:17408
	ds_read_b128 v[172:175], v226 offset:18432
	ds_read_b128 v[176:179], v226 offset:19456
	ds_read_b128 v[180:183], v226 offset:20480
	ds_read_b128 v[228:231], v226 offset:21504
	ds_read_b128 v[232:235], v226 offset:22528
	ds_read_b128 v[236:239], v226 offset:23552
	global_load_lds_dwordx4 v[204:205], off
	v_lshl_add_u64 v[240:241], s[8:9], 0, v[198:199]
	s_mov_b32 m0, s31
	s_addc_u32 s83, s9, 0
	v_readfirstlane_b32 s31, v214
	global_load_lds_dwordx4 v[240:241], off
	v_lshl_add_u64 v[242:243], s[82:83], 0, v[196:197]
	s_mov_b32 m0, s31
	v_readfirstlane_b32 s31, v215
	global_load_lds_dwordx4 v[242:243], off
	v_lshl_add_u64 v[242:243], s[82:83], 0, v[198:199]
	s_mov_b32 m0, s31
	v_readfirstlane_b32 s31, v211
	global_load_lds_dwordx4 v[242:243], off
	v_lshl_add_u64 v[242:243], s[76:77], 0, v[184:185]
	s_mov_b32 m0, s31
	v_readfirstlane_b32 s31, v216
	global_load_lds_dwordx4 v[242:243], off
	v_lshl_add_u64 v[244:245], s[76:77], 0, v[186:187]
	s_mov_b32 m0, s31
	s_nop 0
	global_load_lds_dwordx4 v[244:245], off
	s_waitcnt vmcnt(8)
	s_waitcnt lgkmcnt(0)
	s_barrier
; #define WAIT_V(n) asm volatile("s_waitcnt vmcnt(" #n ")" ::: "memory")
; #define WAIT_L(n) asm volatile("s_waitcnt lgkmcnt(" #n ")" ::: "memory")
; #define BAR __builtin_amdgcn_s_barrier()
; #define SCHED __builtin_amdgcn_sched_barrier(0)
; #define STG_A(b, h, ptr) do { const char* _g = (ptr) + (h) * ahalf; LAS unsigned char* _l = lw + ((b) * 2 + (h)) * 16384; GLDS(_g + voa0, _l); GLDS(_g + voa1, _l + 8192); } while (0)
; #define STG_B(b, h, ptr) do { const char* _g = (ptr) + (h) * bhalf; LAS unsigned char* _l = lw + 65536 + ((b) * 2 + (h)) * 16384; GLDS(_g + vob0, _l); GLDS(_g + vob1, _l + 8192); } while (0)
; #define LDA(dst, b, h) _Pragma("unroll") for (int m = 0; m < 4; ++m) _Pragma("unroll") for (int k = 0; k < 2; ++k) dst[m][k] = *(const LAS bf16x8*)(la + ((b) * 2 + (h)) * 16384 + m * 2048 + k * 1024)
; #define LDB(dst, b, h) _Pragma("unroll") for (int n = 0; n < 2; ++n) _Pragma("unroll") for (int k = 0; k < 2; ++k) dst[n][k] = *(const LAS bf16x8*)(lb + ((b) * 2 + (h)) * 16384 + n * 2048 + k * 1024)
; #define MMA(ai, bj, Af, Bf) do { __builtin_amdgcn_s_setprio(1); \
;     _Pragma("unroll") for (int m = 0; m < 4; ++m) _Pragma("unroll") for (int n = 0; n < 2; ++n) _Pragma("unroll") for (int k = 0; k < 2; ++k) \
;         acc[ai][bj][m][n] = __builtin_amdgcn_mfma_f32_16x16x32_bf16(Bf[n][k], Af[m][k], acc[ai][bj][m][n], 0, 0, 0); \
;     __builtin_amdgcn_s_setprio(0); } while (0)
; template <int BMODE, class Epi, class TileFn>
; DEV void gemm_loop(LAS unsigned char* lds, const bf16_t* __restrict__ A, int lda, const bf16_t* __restrict__ B, int ldb, int K, const Epi& epi, int t0, int tstep, int tend, const TileFn& tf) {
;     ...
;         for (int t = 0; t < nt; t += 2) {
;             const bool last = (t == nt - 2);
;             const char* a1 = cA + (size_t)(t + 1) * 128;
;             const char* a2 = last ? nA : cA + (size_t)(t + 2) * 128;
;             const char* b2 = last ? nB : cB + (size_t)(t + 2) * bks;
;             const char* a3 = a2 + 128; const char* b3 = b2 + bks;
;             LDB(B0, 0, 0); LDB(B1, 0, 1); SCHED; LDA(At, 0, 0); STG_A(1, 1, a1);
;             WAIT_V(8); WAIT_L(0); BAR; MMA(0, 0, At, B0); MMA(0, 1, At, B1); BAR; SCHED;
;             LDA(At, 0, 1); STG_B(0, 0, b2); STG_B(0, 1, b2); STG_A(0, 0, a2);
;             WAIT_V(8); WAIT_L(0); BAR; MMA(1, 0, At, B0); MMA(1, 1, At, B1); BAR; SCHED;
	s_setprio 0
	v_mfma_f32_16x16x32_bf16 v[60:63], v[132:135], v[164:167], 0
	v_mfma_f32_16x16x32_bf16 v[56:59], v[140:143], v[164:167], 0
	v_mfma_f32_16x16x32_bf16 v[44:47], v[132:135], v[172:175], 0
	v_mfma_f32_16x16x32_bf16 v[40:43], v[140:143], v[172:175], 0
	v_mfma_f32_16x16x32_bf16 v[28:31], v[132:135], v[180:183], 0
	v_mfma_f32_16x16x32_bf16 v[24:27], v[140:143], v[180:183], 0
	v_mfma_f32_16x16x32_bf16 v[12:15], v[132:135], v[232:235], 0
	v_mfma_f32_16x16x32_bf16 v[8:11], v[140:143], v[232:235], 0
	v_mfma_f32_16x16x32_bf16 v[60:63], v[136:139], v[168:171], v[60:63]
	v_mfma_f32_16x16x32_bf16 v[56:59], v[144:147], v[168:171], v[56:59]
	v_mfma_f32_16x16x32_bf16 v[44:47], v[136:139], v[176:179], v[44:47]
	v_mfma_f32_16x16x32_bf16 v[40:43], v[144:147], v[176:179], v[40:43]
	v_mfma_f32_16x16x32_bf16 v[28:31], v[136:139], v[228:231], v[28:31]
	v_mfma_f32_16x16x32_bf16 v[24:27], v[144:147], v[228:231], v[24:27]
	v_mfma_f32_16x16x32_bf16 v[12:15], v[136:139], v[236:239], v[12:15]
	v_mfma_f32_16x16x32_bf16 v[8:11], v[144:147], v[236:239], v[8:11]
	v_mfma_f32_16x16x32_bf16 v[52:55], v[148:151], v[164:167], 0
	v_mfma_f32_16x16x32_bf16 v[48:51], v[156:159], v[164:167], 0
	v_mfma_f32_16x16x32_bf16 v[36:39], v[148:151], v[172:175], 0
	v_mfma_f32_16x16x32_bf16 v[32:35], v[156:159], v[172:175], 0
	v_mfma_f32_16x16x32_bf16 v[20:23], v[148:151], v[180:183], 0
	v_mfma_f32_16x16x32_bf16 v[16:19], v[156:159], v[180:183], 0
	v_mfma_f32_16x16x32_bf16 v[4:7], v[148:151], v[232:235], 0
	v_mfma_f32_16x16x32_bf16 v[0:3], v[156:159], v[232:235], 0
	v_mfma_f32_16x16x32_bf16 v[52:55], v[152:155], v[168:171], v[52:55]
	v_mfma_f32_16x16x32_bf16 v[48:51], v[160:163], v[168:171], v[48:51]
	v_mfma_f32_16x16x32_bf16 v[36:39], v[152:155], v[176:179], v[36:39]
	v_mfma_f32_16x16x32_bf16 v[32:35], v[160:163], v[176:179], v[32:35]
	v_mfma_f32_16x16x32_bf16 v[20:23], v[152:155], v[228:231], v[20:23]
	v_mfma_f32_16x16x32_bf16 v[16:19], v[160:163], v[228:231], v[16:19]
	v_mfma_f32_16x16x32_bf16 v[4:7], v[152:155], v[236:239], v[4:7]
	v_mfma_f32_16x16x32_bf16 v[0:3], v[160:163], v[236:239], v[0:3]
	s_barrier
	s_setprio 1
	s_branch .Lkmid_1239
.LBB0_1239:
	ds_read_b128 v[132:135], v225
	ds_read_b128 v[136:139], v225 offset:1024
	ds_read_b128 v[140:143], v225 offset:2048
	ds_read_b128 v[144:147], v225 offset:3072
	ds_read_b128 v[148:151], v225 offset:16384
	ds_read_b128 v[152:155], v225 offset:17408
	ds_read_b128 v[156:159], v225 offset:18432
	ds_read_b128 v[160:163], v225 offset:19456
	s_add_u32 s8, s49, s0
	s_addc_u32 s9, s50, s1
	s_add_u32 s8, s8, 0x18466100
	s_addc_u32 s9, s9, 0
	s_add_u32 s31, s53, s0
	s_addc_u32 s82, s80, s1
	s_cmpk_eq_i32 s0, 0x700
	s_cselect_b32 s77, s29, s9
	s_cselect_b32 s76, s28, s8
	s_cselect_b32 s9, s37, s82
	s_cselect_b32 s8, s30, s31
	v_add_u32_e32 v194, 0xc000, v211
	v_lshl_add_u64 v[204:205], v[120:121], 0, s[0:1]
	v_readfirstlane_b32 s31, v194
	v_add_u32_e32 v194, 0xe000, v211
	s_mov_b32 m0, s31
	v_readfirstlane_b32 s31, v194
	ds_read_b128 v[164:167], v226
	ds_read_b128 v[168:171], v226 offset:1024
	ds_read_b128 v[172:175], v226 offset:2048
	ds_read_b128 v[176:179], v226 offset:3072
	ds_read_b128 v[180:183], v226 offset:4096
	ds_read_b128 v[228:231], v226 offset:5120
	ds_read_b128 v[232:235], v226 offset:6144
	ds_read_b128 v[236:239], v226 offset:7168
	global_load_lds_dwordx4 v[204:205], off
	v_lshl_add_u64 v[204:205], v[122:123], 0, s[0:1]
	s_mov_b32 m0, s31
	s_nop 0
	global_load_lds_dwordx4 v[204:205], off
	s_waitcnt vmcnt(8)
	s_waitcnt lgkmcnt(0)
	s_barrier
	s_setprio 0
	v_mfma_f32_16x16x32_bf16 v[128:131], v[132:135], v[164:167], v[128:131]
	v_mfma_f32_16x16x32_bf16 v[124:127], v[140:143], v[164:167], v[124:127]
	v_mfma_f32_16x16x32_bf16 v[108:111], v[132:135], v[172:175], v[108:111]
	v_mfma_f32_16x16x32_bf16 v[104:107], v[140:143], v[172:175], v[104:107]
	v_mfma_f32_16x16x32_bf16 v[92:95], v[132:135], v[180:183], v[92:95]
	v_mfma_f32_16x16x32_bf16 v[88:91], v[140:143], v[180:183], v[88:91]
	v_mfma_f32_16x16x32_bf16 v[76:79], v[132:135], v[232:235], v[76:79]
	v_mfma_f32_16x16x32_bf16 v[72:75], v[140:143], v[232:235], v[72:75]
	v_mfma_f32_16x16x32_bf16 v[128:131], v[136:139], v[168:171], v[128:131]
	v_mfma_f32_16x16x32_bf16 v[124:127], v[144:147], v[168:171], v[124:127]
	v_mfma_f32_16x16x32_bf16 v[108:111], v[136:139], v[176:179], v[108:111]
	v_mfma_f32_16x16x32_bf16 v[104:107], v[144:147], v[176:179], v[104:107]
	v_mfma_f32_16x16x32_bf16 v[92:95], v[136:139], v[228:231], v[92:95]
	v_mfma_f32_16x16x32_bf16 v[88:91], v[144:147], v[228:231], v[88:91]
	v_mfma_f32_16x16x32_bf16 v[76:79], v[136:139], v[236:239], v[76:79]
	v_mfma_f32_16x16x32_bf16 v[72:75], v[144:147], v[236:239], v[72:75]
	v_mfma_f32_16x16x32_bf16 v[116:119], v[148:151], v[164:167], v[116:119]
	v_mfma_f32_16x16x32_bf16 v[112:115], v[156:159], v[164:167], v[112:115]
	v_mfma_f32_16x16x32_bf16 v[100:103], v[148:151], v[172:175], v[100:103]
	v_mfma_f32_16x16x32_bf16 v[96:99], v[156:159], v[172:175], v[96:99]
	v_mfma_f32_16x16x32_bf16 v[84:87], v[148:151], v[180:183], v[84:87]
	v_mfma_f32_16x16x32_bf16 v[80:83], v[156:159], v[180:183], v[80:83]
	v_mfma_f32_16x16x32_bf16 v[68:71], v[148:151], v[232:235], v[68:71]
	v_mfma_f32_16x16x32_bf16 v[64:67], v[156:159], v[232:235], v[64:67]
	v_mfma_f32_16x16x32_bf16 v[116:119], v[152:155], v[168:171], v[116:119]
	v_mfma_f32_16x16x32_bf16 v[112:115], v[160:163], v[168:171], v[112:115]
	v_mfma_f32_16x16x32_bf16 v[100:103], v[152:155], v[176:179], v[100:103]
	v_mfma_f32_16x16x32_bf16 v[96:99], v[160:163], v[176:179], v[96:99]
	v_mfma_f32_16x16x32_bf16 v[84:87], v[152:155], v[228:231], v[84:87]
	v_mfma_f32_16x16x32_bf16 v[80:83], v[160:163], v[228:231], v[80:83]
	v_mfma_f32_16x16x32_bf16 v[68:71], v[152:155], v[236:239], v[68:71]
	v_mfma_f32_16x16x32_bf16 v[64:67], v[160:163], v[236:239], v[64:67]
	s_barrier
; #define WAIT_V(n) asm volatile("s_waitcnt vmcnt(" #n ")" ::: "memory")
; #define WAIT_L(n) asm volatile("s_waitcnt lgkmcnt(" #n ")" ::: "memory")
; #define BAR __builtin_amdgcn_s_barrier()
; #define SCHED __builtin_amdgcn_sched_barrier(0)
; #define STG_A(b, h, ptr) do { const char* _g = (ptr) + (h) * ahalf; LAS unsigned char* _l = lw + ((b) * 2 + (h)) * 16384; GLDS(_g + voa0, _l); GLDS(_g + voa1, _l + 8192); } while (0)
; #define STG_B(b, h, ptr) do { const char* _g = (ptr) + (h) * bhalf; LAS unsigned char* _l = lw + 65536 + ((b) * 2 + (h)) * 16384; GLDS(_g + vob0, _l); GLDS(_g + vob1, _l + 8192); } while (0)
; #define LDA(dst, b, h) _Pragma("unroll") for (int m = 0; m < 4; ++m) _Pragma("unroll") for (int k = 0; k < 2; ++k) dst[m][k] = *(const LAS bf16x8*)(la + ((b) * 2 + (h)) * 16384 + m * 2048 + k * 1024)
; #define LDB(dst, b, h) _Pragma("unroll") for (int n = 0; n < 2; ++n) _Pragma("unroll") for (int k = 0; k < 2; ++k) dst[n][k] = *(const LAS bf16x8*)(lb + ((b) * 2 + (h)) * 16384 + n * 2048 + k * 1024)
; #define MMA(ai, bj, Af, Bf) do { __builtin_amdgcn_s_setprio(1); \
;     _Pragma("unroll") for (int m = 0; m < 4; ++m) _Pragma("unroll") for (int n = 0; n < 2; ++n) _Pragma("unroll") for (int k = 0; k < 2; ++k) \
;         acc[ai][bj][m][n] = __builtin_amdgcn_mfma_f32_16x16x32_bf16(Bf[n][k], Af[m][k], acc[ai][bj][m][n], 0, 0, 0); \
;     __builtin_amdgcn_s_setprio(0); } while (0)
; template <int BMODE, class Epi, class TileFn>
; DEV void gemm_loop(LAS unsigned char* lds, const bf16_t* __restrict__ A, int lda, const bf16_t* __restrict__ B, int ldb, int K, const Epi& epi, int t0, int tstep, int tend, const TileFn& tf) {
;     ...
;             LDA(At, 0, 1); STG_B(0, 0, b2); STG_B(0, 1, b2); STG_A(0, 0, a2);
;             WAIT_V(8); WAIT_L(0); BAR; MMA(1, 0, At, B0); MMA(1, 1, At, B1); BAR; SCHED;
;             LDB(B0, 1, 0); LDB(B1, 1, 1); SCHED; LDA(At, 1, 0); STG_A(0, 1, a2);
;             WAIT_V(8); WAIT_L(0); BAR; MMA(0, 0, At, B0); MMA(0, 1, At, B1); BAR; SCHED;
	s_setprio 1
	v_readfirstlane_b32 s31, v212
	v_lshl_add_u64 v[204:205], s[8:9], 0, v[196:197]
	s_mov_b32 m0, s31
	v_readfirstlane_b32 s31, v213
	s_add_u32 s82, s8, 0x40000
	ds_read_b128 v[164:167], v226 offset:16384
	ds_read_b128 v[168:171], v226 offset:17408
	ds_read_b128 v[172:175], v226 offset:18432
	ds_read_b128 v[176:179], v226 offset:19456
	ds_read_b128 v[180:183], v226 offset:20480
	ds_read_b128 v[228:231], v226 offset:21504
	ds_read_b128 v[232:235], v226 offset:22528
	ds_read_b128 v[236:239], v226 offset:23552
	global_load_lds_dwordx4 v[204:205], off
	v_lshl_add_u64 v[240:241], s[8:9], 0, v[198:199]
	s_mov_b32 m0, s31
	s_addc_u32 s83, s9, 0
	v_readfirstlane_b32 s31, v214
	global_load_lds_dwordx4 v[240:241], off
	v_lshl_add_u64 v[242:243], s[82:83], 0, v[196:197]
	s_mov_b32 m0, s31
	v_readfirstlane_b32 s31, v215
	global_load_lds_dwordx4 v[242:243], off
	v_lshl_add_u64 v[242:243], s[82:83], 0, v[198:199]
	s_mov_b32 m0, s31
	v_readfirstlane_b32 s31, v211
	global_load_lds_dwordx4 v[242:243], off
	v_lshl_add_u64 v[242:243], s[76:77], 0, v[184:185]
	s_mov_b32 m0, s31
	v_readfirstlane_b32 s31, v216
	global_load_lds_dwordx4 v[242:243], off
	v_lshl_add_u64 v[244:245], s[76:77], 0, v[186:187]
	s_mov_b32 m0, s31
	s_nop 0
	global_load_lds_dwordx4 v[244:245], off
	s_waitcnt vmcnt(8)
	s_waitcnt lgkmcnt(0)
	s_barrier
	s_setprio 0
	v_mfma_f32_16x16x32_bf16 v[60:63], v[132:135], v[164:167], v[60:63]
	v_mfma_f32_16x16x32_bf16 v[56:59], v[140:143], v[164:167], v[56:59]
	v_mfma_f32_16x16x32_bf16 v[44:47], v[132:135], v[172:175], v[44:47]
	v_mfma_f32_16x16x32_bf16 v[40:43], v[140:143], v[172:175], v[40:43]
	v_mfma_f32_16x16x32_bf16 v[28:31], v[132:135], v[180:183], v[28:31]
	v_mfma_f32_16x16x32_bf16 v[24:27], v[140:143], v[180:183], v[24:27]
	v_mfma_f32_16x16x32_bf16 v[12:15], v[132:135], v[232:235], v[12:15]
	v_mfma_f32_16x16x32_bf16 v[8:11], v[140:143], v[232:235], v[8:11]
	v_mfma_f32_16x16x32_bf16 v[60:63], v[136:139], v[168:171], v[60:63]
	v_mfma_f32_16x16x32_bf16 v[56:59], v[144:147], v[168:171], v[56:59]
	v_mfma_f32_16x16x32_bf16 v[44:47], v[136:139], v[176:179], v[44:47]
	v_mfma_f32_16x16x32_bf16 v[40:43], v[144:147], v[176:179], v[40:43]
	v_mfma_f32_16x16x32_bf16 v[28:31], v[136:139], v[228:231], v[28:31]
	v_mfma_f32_16x16x32_bf16 v[24:27], v[144:147], v[228:231], v[24:27]
	v_mfma_f32_16x16x32_bf16 v[12:15], v[136:139], v[236:239], v[12:15]
	v_mfma_f32_16x16x32_bf16 v[8:11], v[144:147], v[236:239], v[8:11]
	v_mfma_f32_16x16x32_bf16 v[52:55], v[148:151], v[164:167], v[52:55]
	v_mfma_f32_16x16x32_bf16 v[48:51], v[156:159], v[164:167], v[48:51]
	v_mfma_f32_16x16x32_bf16 v[36:39], v[148:151], v[172:175], v[36:39]
	v_mfma_f32_16x16x32_bf16 v[32:35], v[156:159], v[172:175], v[32:35]
	v_mfma_f32_16x16x32_bf16 v[20:23], v[148:151], v[180:183], v[20:23]
	v_mfma_f32_16x16x32_bf16 v[16:19], v[156:159], v[180:183], v[16:19]
	v_mfma_f32_16x16x32_bf16 v[4:7], v[148:151], v[232:235], v[4:7]
	v_mfma_f32_16x16x32_bf16 v[0:3], v[156:159], v[232:235], v[0:3]
	v_mfma_f32_16x16x32_bf16 v[52:55], v[152:155], v[168:171], v[52:55]
	v_mfma_f32_16x16x32_bf16 v[48:51], v[160:163], v[168:171], v[48:51]
	v_mfma_f32_16x16x32_bf16 v[36:39], v[152:155], v[176:179], v[36:39]
	v_mfma_f32_16x16x32_bf16 v[32:35], v[160:163], v[176:179], v[32:35]
	v_mfma_f32_16x16x32_bf16 v[20:23], v[152:155], v[228:231], v[20:23]
	v_mfma_f32_16x16x32_bf16 v[16:19], v[160:163], v[228:231], v[16:19]
	v_mfma_f32_16x16x32_bf16 v[4:7], v[152:155], v[236:239], v[4:7]
	v_mfma_f32_16x16x32_bf16 v[0:3], v[160:163], v[236:239], v[0:3]
	s_barrier
	s_setprio 1
.Lkmid_1239:
	ds_read_b128 v[132:135], v225 offset:32768
	ds_read_b128 v[136:139], v225 offset:33792
	ds_read_b128 v[140:143], v225 offset:34816
	ds_read_b128 v[144:147], v225 offset:35840
	ds_read_b128 v[148:151], v225 offset:49152
	ds_read_b128 v[152:155], v225 offset:50176
	ds_read_b128 v[156:159], v225 offset:51200
	ds_read_b128 v[160:163], v225 offset:52224
	s_add_u32 s76, s76, 0x40000
	s_addc_u32 s77, s77, 0
	v_readfirstlane_b32 s31, v217
	v_lshl_add_u64 v[246:247], s[76:77], 0, v[184:185]
	s_mov_b32 m0, s31
	v_readfirstlane_b32 s31, v218
	ds_read_b128 v[164:167], v226 offset:32768
	ds_read_b128 v[168:171], v226 offset:33792
	ds_read_b128 v[172:175], v226 offset:34816
	ds_read_b128 v[176:179], v226 offset:35840
	ds_read_b128 v[180:183], v226 offset:36864
	ds_read_b128 v[228:231], v226 offset:37888
	ds_read_b128 v[232:235], v226 offset:38912
	ds_read_b128 v[236:239], v226 offset:39936
	global_load_lds_dwordx4 v[246:247], off
	v_lshl_add_u64 v[246:247], s[76:77], 0, v[186:187]
	s_mov_b32 m0, s31
	s_nop 0
	global_load_lds_dwordx4 v[246:247], off
	s_waitcnt vmcnt(8)
	s_waitcnt lgkmcnt(0)
	s_barrier
; #define WAIT_V(n) asm volatile("s_waitcnt vmcnt(" #n ")" ::: "memory")
; #define WAIT_L(n) asm volatile("s_waitcnt lgkmcnt(" #n ")" ::: "memory")
; #define BAR __builtin_amdgcn_s_barrier()
; #define SCHED __builtin_amdgcn_sched_barrier(0)
; #define STG_A(b, h, ptr) do { const char* _g = (ptr) + (h) * ahalf; LAS unsigned char* _l = lw + ((b) * 2 + (h)) * 16384; GLDS(_g + voa0, _l); GLDS(_g + voa1, _l + 8192); } while (0)
; #define STG_B(b, h, ptr) do { const char* _g = (ptr) + (h) * bhalf; LAS unsigned char* _l = lw + 65536 + ((b) * 2 + (h)) * 16384; GLDS(_g + vob0, _l); GLDS(_g + vob1, _l + 8192); } while (0)
; #define LDA(dst, b, h) _Pragma("unroll") for (int m = 0; m < 4; ++m) _Pragma("unroll") for (int k = 0; k < 2; ++k) dst[m][k] = *(const LAS bf16x8*)(la + ((b) * 2 + (h)) * 16384 + m * 2048 + k * 1024)
; #define MMA(ai, bj, Af, Bf) do { __builtin_amdgcn_s_setprio(1); \
;     _Pragma("unroll") for (int m = 0; m < 4; ++m) _Pragma("unroll") for (int n = 0; n < 2; ++n) _Pragma("unroll") for (int k = 0; k < 2; ++k) \
;         acc[ai][bj][m][n] = __builtin_amdgcn_mfma_f32_16x16x32_bf16(Bf[n][k], Af[m][k], acc[ai][bj][m][n], 0, 0, 0); \
;     __builtin_amdgcn_s_setprio(0); } while (0)
; template <int BMODE, class Epi, class TileFn>
; DEV void gemm_loop(LAS unsigned char* lds, const bf16_t* __restrict__ A, int lda, const bf16_t* __restrict__ B, int ldb, int K, const Epi& epi, int t0, int tstep, int tend, const TileFn& tf) {
;     ...
;             WAIT_V(8); WAIT_L(0); BAR; MMA(0, 0, At, B0); MMA(0, 1, At, B1); BAR; SCHED;
;             LDA(At, 1, 1); STG_B(1, 0, b3); STG_B(1, 1, b3); STG_A(1, 0, a3);
;             WAIT_V(8); WAIT_L(0); BAR; MMA(1, 0, At, B0); MMA(1, 1, At, B1); BAR; SCHED;
;         }
	s_setprio 0
	v_mfma_f32_16x16x32_bf16 v[128:131], v[132:135], v[164:167], v[128:131]
	v_mfma_f32_16x16x32_bf16 v[124:127], v[140:143], v[164:167], v[124:127]
	v_mfma_f32_16x16x32_bf16 v[108:111], v[132:135], v[172:175], v[108:111]
	v_mfma_f32_16x16x32_bf16 v[104:107], v[140:143], v[172:175], v[104:107]
	v_mfma_f32_16x16x32_bf16 v[92:95], v[132:135], v[180:183], v[92:95]
	v_mfma_f32_16x16x32_bf16 v[88:91], v[140:143], v[180:183], v[88:91]
	v_mfma_f32_16x16x32_bf16 v[76:79], v[132:135], v[232:235], v[76:79]
	v_mfma_f32_16x16x32_bf16 v[72:75], v[140:143], v[232:235], v[72:75]
	v_mfma_f32_16x16x32_bf16 v[128:131], v[136:139], v[168:171], v[128:131]
	v_mfma_f32_16x16x32_bf16 v[124:127], v[144:147], v[168:171], v[124:127]
	v_mfma_f32_16x16x32_bf16 v[108:111], v[136:139], v[176:179], v[108:111]
	v_mfma_f32_16x16x32_bf16 v[104:107], v[144:147], v[176:179], v[104:107]
	v_mfma_f32_16x16x32_bf16 v[92:95], v[136:139], v[228:231], v[92:95]
	v_mfma_f32_16x16x32_bf16 v[88:91], v[144:147], v[228:231], v[88:91]
	v_mfma_f32_16x16x32_bf16 v[76:79], v[136:139], v[236:239], v[76:79]
	v_mfma_f32_16x16x32_bf16 v[72:75], v[144:147], v[236:239], v[72:75]
	v_mfma_f32_16x16x32_bf16 v[116:119], v[148:151], v[164:167], v[116:119]
	v_mfma_f32_16x16x32_bf16 v[112:115], v[156:159], v[164:167], v[112:115]
	v_mfma_f32_16x16x32_bf16 v[100:103], v[148:151], v[172:175], v[100:103]
	v_mfma_f32_16x16x32_bf16 v[96:99], v[156:159], v[172:175], v[96:99]
	v_mfma_f32_16x16x32_bf16 v[84:87], v[148:151], v[180:183], v[84:87]
	v_mfma_f32_16x16x32_bf16 v[80:83], v[156:159], v[180:183], v[80:83]
	v_mfma_f32_16x16x32_bf16 v[68:71], v[148:151], v[232:235], v[68:71]
	v_mfma_f32_16x16x32_bf16 v[64:67], v[156:159], v[232:235], v[64:67]
	v_mfma_f32_16x16x32_bf16 v[116:119], v[152:155], v[168:171], v[116:119]
	v_mfma_f32_16x16x32_bf16 v[112:115], v[160:163], v[168:171], v[112:115]
	v_mfma_f32_16x16x32_bf16 v[100:103], v[152:155], v[176:179], v[100:103]
	v_mfma_f32_16x16x32_bf16 v[96:99], v[160:163], v[176:179], v[96:99]
	v_mfma_f32_16x16x32_bf16 v[84:87], v[152:155], v[228:231], v[84:87]
	v_mfma_f32_16x16x32_bf16 v[80:83], v[160:163], v[228:231], v[80:83]
	v_mfma_f32_16x16x32_bf16 v[68:71], v[152:155], v[236:239], v[68:71]
	v_mfma_f32_16x16x32_bf16 v[64:67], v[160:163], v[236:239], v[64:67]
	s_barrier
	s_setprio 1
	v_readfirstlane_b32 s31, v219
	v_lshl_add_u64 v[204:205], v[204:205], 0, s[2:3]
	s_mov_b32 m0, s31
	v_readfirstlane_b32 s31, v220
	s_add_u32 s8, s8, 0x40080
	ds_read_b128 v[164:167], v226 offset:49152
	ds_read_b128 v[168:171], v226 offset:50176
	ds_read_b128 v[172:175], v226 offset:51200
	ds_read_b128 v[176:179], v226 offset:52224
	ds_read_b128 v[180:183], v226 offset:53248
	ds_read_b128 v[228:231], v226 offset:54272
	ds_read_b128 v[232:235], v226 offset:55296
	ds_read_b128 v[236:239], v226 offset:56320
	global_load_lds_dwordx4 v[204:205], off
	v_lshl_add_u64 v[204:205], v[240:241], 0, s[2:3]
	s_mov_b32 m0, s31
	s_addc_u32 s9, s9, 0
	v_readfirstlane_b32 s31, v223
	global_load_lds_dwordx4 v[204:205], off
	v_lshl_add_u64 v[204:205], s[8:9], 0, v[196:197]
	s_mov_b32 m0, s31
	s_nop 0
	global_load_lds_dwordx4 v[204:205], off
	v_lshl_add_u64 v[204:205], s[8:9], 0, v[198:199]
	v_readfirstlane_b32 s8, v224
	s_mov_b32 m0, s8
	v_readfirstlane_b32 s8, v221
	global_load_lds_dwordx4 v[204:205], off
	v_lshl_add_u64 v[204:205], v[242:243], 0, s[2:3]
	s_mov_b32 m0, s8
	v_readfirstlane_b32 s8, v222
	global_load_lds_dwordx4 v[204:205], off
	v_lshl_add_u64 v[204:205], v[244:245], 0, s[2:3]
	s_mov_b32 m0, s8
	s_nop 0
	global_load_lds_dwordx4 v[204:205], off
	s_waitcnt vmcnt(8)
	s_waitcnt lgkmcnt(0)
	s_barrier
	s_setprio 0
	v_mfma_f32_16x16x32_bf16 v[60:63], v[132:135], v[164:167], v[60:63]
	v_mfma_f32_16x16x32_bf16 v[56:59], v[140:143], v[164:167], v[56:59]
	v_mfma_f32_16x16x32_bf16 v[44:47], v[132:135], v[172:175], v[44:47]
	v_mfma_f32_16x16x32_bf16 v[40:43], v[140:143], v[172:175], v[40:43]
	v_mfma_f32_16x16x32_bf16 v[28:31], v[132:135], v[180:183], v[28:31]
	v_mfma_f32_16x16x32_bf16 v[24:27], v[140:143], v[180:183], v[24:27]
	v_mfma_f32_16x16x32_bf16 v[12:15], v[132:135], v[232:235], v[12:15]
	v_mfma_f32_16x16x32_bf16 v[8:11], v[140:143], v[232:235], v[8:11]
	v_mfma_f32_16x16x32_bf16 v[60:63], v[136:139], v[168:171], v[60:63]
	v_mfma_f32_16x16x32_bf16 v[56:59], v[144:147], v[168:171], v[56:59]
	v_mfma_f32_16x16x32_bf16 v[44:47], v[136:139], v[176:179], v[44:47]
	v_mfma_f32_16x16x32_bf16 v[40:43], v[144:147], v[176:179], v[40:43]
	v_mfma_f32_16x16x32_bf16 v[28:31], v[136:139], v[228:231], v[28:31]
	v_mfma_f32_16x16x32_bf16 v[24:27], v[144:147], v[228:231], v[24:27]
	v_mfma_f32_16x16x32_bf16 v[12:15], v[136:139], v[236:239], v[12:15]
	v_mfma_f32_16x16x32_bf16 v[8:11], v[144:147], v[236:239], v[8:11]
	v_mfma_f32_16x16x32_bf16 v[52:55], v[148:151], v[164:167], v[52:55]
	v_mfma_f32_16x16x32_bf16 v[48:51], v[156:159], v[164:167], v[48:51]
	v_mfma_f32_16x16x32_bf16 v[36:39], v[148:151], v[172:175], v[36:39]
	v_mfma_f32_16x16x32_bf16 v[32:35], v[156:159], v[172:175], v[32:35]
	v_mfma_f32_16x16x32_bf16 v[20:23], v[148:151], v[180:183], v[20:23]
	v_mfma_f32_16x16x32_bf16 v[16:19], v[156:159], v[180:183], v[16:19]
	v_mfma_f32_16x16x32_bf16 v[4:7], v[148:151], v[232:235], v[4:7]
	v_mfma_f32_16x16x32_bf16 v[0:3], v[156:159], v[232:235], v[0:3]
	v_mfma_f32_16x16x32_bf16 v[52:55], v[152:155], v[168:171], v[52:55]
	v_mfma_f32_16x16x32_bf16 v[48:51], v[160:163], v[168:171], v[48:51]
	v_mfma_f32_16x16x32_bf16 v[36:39], v[152:155], v[176:179], v[36:39]
	v_mfma_f32_16x16x32_bf16 v[32:35], v[160:163], v[176:179], v[32:35]
	v_mfma_f32_16x16x32_bf16 v[20:23], v[152:155], v[228:231], v[20:23]
	v_mfma_f32_16x16x32_bf16 v[16:19], v[160:163], v[228:231], v[16:19]
	v_mfma_f32_16x16x32_bf16 v[4:7], v[152:155], v[236:239], v[4:7]
	v_mfma_f32_16x16x32_bf16 v[0:3], v[160:163], v[236:239], v[0:3]
	s_barrier
	s_setprio 1
	s_add_i32 s81, s81, 2
	s_add_u32 s0, s0, 0x100
	s_addc_u32 s1, s1, 0
	s_cmp_gt_u32 s81, 13
	s_cbranch_scc0 .LBB0_1239
	s_setprio 0
	s_and_saveexec_b64 s[0:1], s[44:45]
	s_cbranch_execz .LBB0_1242
	s_barrier

; #define WAIT_V(n) asm volatile("s_waitcnt vmcnt(" #n ")" ::: "memory")
; #define WAIT_L(n) asm volatile("s_waitcnt lgkmcnt(" #n ")" ::: "memory")
; #define BAR __builtin_amdgcn_s_barrier()
; #define SCHED __builtin_amdgcn_sched_barrier(0)
; #define STG_A(b, h, ptr) do { const char* _g = (ptr) + (h) * ahalf; LAS unsigned char* _l = lw + ((b) * 2 + (h)) * 16384; GLDS(_g + voa0, _l); GLDS(_g + voa1, _l + 8192); } while (0)
; #define STG_B(b, h, ptr) do { const char* _g = (ptr) + (h) * bhalf; LAS unsigned char* _l = lw + 65536 + ((b) * 2 + (h)) * 16384; GLDS(_g + vob0, _l); GLDS(_g + vob1, _l + 8192); } while (0)
; #define LDA(dst, b, h) _Pragma("unroll") for (int m = 0; m < 4; ++m) _Pragma("unroll") for (int k = 0; k < 2; ++k) dst[m][k] = *(const LAS bf16x8*)(la + ((b) * 2 + (h)) * 16384 + m * 2048 + k * 1024)
; #define LDB(dst, b, h) _Pragma("unroll") for (int n = 0; n < 2; ++n) _Pragma("unroll") for (int k = 0; k < 2; ++k) dst[n][k] = *(const LAS bf16x8*)(lb + ((b) * 2 + (h)) * 16384 + n * 2048 + k * 1024)
; template <int BMODE, class Epi, class TileFn>
; DEV void gemm_loop(LAS unsigned char* lds, const bf16_t* __restrict__ A, int lda, const bf16_t* __restrict__ B, int ldb, int K, const Epi& epi, int t0, int tstep, int tend, const TileFn& tf) {
;     ...
;     for (int tt = t0;; tt += tstep, par ^= 1) {
;         const bool has_next = tt + tstep < tend;
;         epi.prefetch(lds, brow, par, tid);
;         int nrow = brow, ncol = bcol;
;         if (has_next) tf(tt + tstep, nrow, ncol);
;         const char* nA = (const char*)(A + (size_t)nrow * lda);
;         const char* nB = BMODE == 0 ? (const char*)(B + (size_t)ncol * ldb) : (const char*)(B + (size_t)ncol * 8);
;         for (int t = 0; t < nt; t += 2) {
;             const bool last = (t == nt - 2);
;             const char* a1 = cA + (size_t)(t + 1) * 128;
;             const char* a2 = last ? nA : cA + (size_t)(t + 2) * 128;
;             const char* b2 = last ? nB : cB + (size_t)(t + 2) * bks;
;             const char* a3 = a2 + 128; const char* b3 = b2 + bks;
;             LDB(B0, 0, 0); LDB(B1, 0, 1); SCHED; LDA(At, 0, 0); STG_A(1, 1, a1);
;             WAIT_V(8); WAIT_L(0); BAR; MMA(0, 0, At, B0); MMA(0, 1, At, B1); BAR; SCHED;
;             LDA(At, 0, 1); STG_B(0, 0, b2); STG_B(0, 1, b2); STG_A(0, 0, a2);
;             WAIT_V(8); WAIT_L(0); BAR; MMA(1, 0, At, B0); MMA(1, 1, At, B1); BAR; SCHED;
.LBB0_1337:
	s_ashr_i32 s53, s52, 31
	s_lshl_b64 s[82:83], s[52:53], 11
	s_add_u32 s30, s72, s82
	s_addc_u32 s50, s73, s83
	s_ashr_i32 s81, s80, 31
	s_lshl_b64 s[40:41], s[80:81], 11
	s_add_u32 s53, s48, s40
	s_addc_u32 s74, s49, s41
	s_add_u32 s75, s66, s36
	s_addc_u32 s81, s67, s37
	v_readlane_b32 s31, v254, 63
	s_add_u32 s92, s31, s8
	v_readlane_b32 s8, v250, 0
	v_lshl_add_u64 v[136:137], v[132:133], 0, s[36:37]
	v_lshl_add_u64 v[138:139], v[134:135], 0, s[36:37]
	s_addc_u32 s93, s8, s9
	s_mov_b32 s94, -2
	s_mov_b64 s[36:37], 0
	s_setprio 1
	ds_read_b128 v[158:161], v156
	ds_read_b128 v[162:165], v156 offset:1024
	ds_read_b128 v[166:169], v156 offset:2048
	ds_read_b128 v[170:173], v156 offset:3072
	ds_read_b128 v[174:177], v156 offset:16384
	ds_read_b128 v[178:181], v156 offset:17408
	ds_read_b128 v[182:185], v156 offset:18432
	ds_read_b128 v[196:199], v156 offset:19456
	s_add_u32 s8, s75, s36
	s_addc_u32 s9, s81, s37
	s_add_u32 s8, s8, 0x62e6100
	s_addc_u32 s9, s9, 0
	s_add_u32 s31, s92, s36
	s_addc_u32 s95, s93, s37
	s_cmpk_eq_i32 s36, 0x700
	s_cselect_b32 s55, s50, s9
	s_cselect_b32 s54, s30, s8
	s_cselect_b32 s9, s74, s95
	s_cselect_b32 s8, s53, s31
	v_add_u32_e32 v194, 0xc000, v141
	v_lshl_add_u64 v[186:187], v[136:137], 0, s[36:37]
	v_readfirstlane_b32 s31, v194
	v_add_u32_e32 v194, 0xe000, v141
	s_mov_b32 m0, s31
	v_readfirstlane_b32 s31, v194
	ds_read_b128 v[200:203], v157
	ds_read_b128 v[212:215], v157 offset:1024
	ds_read_b128 v[216:219], v157 offset:2048
	ds_read_b128 v[220:223], v157 offset:3072
	ds_read_b128 v[224:227], v157 offset:4096
	ds_read_b128 v[228:231], v157 offset:5120
	ds_read_b128 v[232:235], v157 offset:6144
	ds_read_b128 v[236:239], v157 offset:7168
	global_load_lds_dwordx4 v[186:187], off
	v_lshl_add_u64 v[186:187], v[138:139], 0, s[36:37]
	s_mov_b32 m0, s31
	s_nop 0
	global_load_lds_dwordx4 v[186:187], off
	s_waitcnt vmcnt(8)
	s_waitcnt lgkmcnt(0)
	s_barrier
	s_setprio 0
	v_mfma_f32_16x16x32_bf16 v[124:127], v[158:161], v[200:203], 0
	v_mfma_f32_16x16x32_bf16 v[120:123], v[166:169], v[200:203], 0
	v_mfma_f32_16x16x32_bf16 v[104:107], v[158:161], v[216:219], 0
	v_mfma_f32_16x16x32_bf16 v[108:111], v[166:169], v[216:219], 0
	v_mfma_f32_16x16x32_bf16 v[92:95], v[158:161], v[224:227], 0
	v_mfma_f32_16x16x32_bf16 v[88:91], v[166:169], v[224:227], 0
	v_mfma_f32_16x16x32_bf16 v[72:75], v[158:161], v[232:235], 0
	v_mfma_f32_16x16x32_bf16 v[76:79], v[166:169], v[232:235], 0
	v_mfma_f32_16x16x32_bf16 v[124:127], v[162:165], v[212:215], v[124:127]
	v_mfma_f32_16x16x32_bf16 v[120:123], v[170:173], v[212:215], v[120:123]
	v_mfma_f32_16x16x32_bf16 v[104:107], v[162:165], v[220:223], v[104:107]
	v_mfma_f32_16x16x32_bf16 v[108:111], v[170:173], v[220:223], v[108:111]
	v_mfma_f32_16x16x32_bf16 v[92:95], v[162:165], v[228:231], v[92:95]
	v_mfma_f32_16x16x32_bf16 v[88:91], v[170:173], v[228:231], v[88:91]
	v_mfma_f32_16x16x32_bf16 v[72:75], v[162:165], v[236:239], v[72:75]
	v_mfma_f32_16x16x32_bf16 v[76:79], v[170:173], v[236:239], v[76:79]
	v_mfma_f32_16x16x32_bf16 v[116:119], v[174:177], v[200:203], 0
	v_mfma_f32_16x16x32_bf16 v[112:115], v[182:185], v[200:203], 0
	v_mfma_f32_16x16x32_bf16 v[96:99], v[174:177], v[216:219], 0
	v_mfma_f32_16x16x32_bf16 v[100:103], v[182:185], v[216:219], 0
	v_mfma_f32_16x16x32_bf16 v[84:87], v[174:177], v[224:227], 0
	v_mfma_f32_16x16x32_bf16 v[80:83], v[182:185], v[224:227], 0
	v_mfma_f32_16x16x32_bf16 v[64:67], v[174:177], v[232:235], 0
	v_mfma_f32_16x16x32_bf16 v[68:71], v[182:185], v[232:235], 0
	v_mfma_f32_16x16x32_bf16 v[116:119], v[178:181], v[212:215], v[116:119]
	v_mfma_f32_16x16x32_bf16 v[112:115], v[196:199], v[212:215], v[112:115]
	v_mfma_f32_16x16x32_bf16 v[96:99], v[178:181], v[220:223], v[96:99]
	v_mfma_f32_16x16x32_bf16 v[100:103], v[196:199], v[220:223], v[100:103]
	v_mfma_f32_16x16x32_bf16 v[84:87], v[178:181], v[228:231], v[84:87]
	v_mfma_f32_16x16x32_bf16 v[80:83], v[196:199], v[228:231], v[80:83]
	v_mfma_f32_16x16x32_bf16 v[64:67], v[178:181], v[236:239], v[64:67]
	v_mfma_f32_16x16x32_bf16 v[68:71], v[196:199], v[236:239], v[68:71]
	s_barrier
	s_setprio 1
	v_readfirstlane_b32 s31, v142
	v_lshl_add_u64 v[186:187], s[8:9], 0, v[128:129]
	s_mov_b32 m0, s31
	v_readfirstlane_b32 s31, v143
	s_add_u32 s96, s8, 0x40000
	ds_read_b128 v[200:203], v157 offset:16384
	ds_read_b128 v[212:215], v157 offset:17408
	ds_read_b128 v[216:219], v157 offset:18432
	ds_read_b128 v[220:223], v157 offset:19456
	ds_read_b128 v[224:227], v157 offset:20480
	ds_read_b128 v[228:231], v157 offset:21504
	ds_read_b128 v[232:235], v157 offset:22528
	ds_read_b128 v[236:239], v157 offset:23552
	global_load_lds_dwordx4 v[186:187], off
	v_lshl_add_u64 v[204:205], s[8:9], 0, v[130:131]
	s_mov_b32 m0, s31
	s_addc_u32 s97, s9, 0
	v_readfirstlane_b32 s31, v144
	global_load_lds_dwordx4 v[204:205], off
	v_lshl_add_u64 v[240:241], s[96:97], 0, v[128:129]
	s_mov_b32 m0, s31
	v_readfirstlane_b32 s31, v145
	global_load_lds_dwordx4 v[240:241], off
	v_lshl_add_u64 v[240:241], s[96:97], 0, v[130:131]
	s_mov_b32 m0, s31
	v_readfirstlane_b32 s31, v141
	global_load_lds_dwordx4 v[240:241], off
	v_lshl_add_u64 v[240:241], s[54:55], 0, v[128:129]
	s_mov_b32 m0, s31
	v_readfirstlane_b32 s31, v146
	global_load_lds_dwordx4 v[240:241], off
	v_lshl_add_u64 v[242:243], s[54:55], 0, v[130:131]
	s_mov_b32 m0, s31
	s_nop 0
	global_load_lds_dwordx4 v[242:243], off
	s_waitcnt vmcnt(8)
	s_waitcnt lgkmcnt(0)
	s_barrier
; #define WAIT_V(n) asm volatile("s_waitcnt vmcnt(" #n ")" ::: "memory")
; #define WAIT_L(n) asm volatile("s_waitcnt lgkmcnt(" #n ")" ::: "memory")
; #define BAR __builtin_amdgcn_s_barrier()
; #define SCHED __builtin_amdgcn_sched_barrier(0)
; #define STG_A(b, h, ptr) do { const char* _g = (ptr) + (h) * ahalf; LAS unsigned char* _l = lw + ((b) * 2 + (h)) * 16384; GLDS(_g + voa0, _l); GLDS(_g + voa1, _l + 8192); } while (0)
; #define STG_B(b, h, ptr) do { const char* _g = (ptr) + (h) * bhalf; LAS unsigned char* _l = lw + 65536 + ((b) * 2 + (h)) * 16384; GLDS(_g + vob0, _l); GLDS(_g + vob1, _l + 8192); } while (0)
; #define LDA(dst, b, h) _Pragma("unroll") for (int m = 0; m < 4; ++m) _Pragma("unroll") for (int k = 0; k < 2; ++k) dst[m][k] = *(const LAS bf16x8*)(la + ((b) * 2 + (h)) * 16384 + m * 2048 + k * 1024)
; #define LDB(dst, b, h) _Pragma("unroll") for (int n = 0; n < 2; ++n) _Pragma("unroll") for (int k = 0; k < 2; ++k) dst[n][k] = *(const LAS bf16x8*)(lb + ((b) * 2 + (h)) * 16384 + n * 2048 + k * 1024)
; #define MMA(ai, bj, Af, Bf) do { __builtin_amdgcn_s_setprio(1); \
;     _Pragma("unroll") for (int m = 0; m < 4; ++m) _Pragma("unroll") for (int n = 0; n < 2; ++n) _Pragma("unroll") for (int k = 0; k < 2; ++k) \
;         acc[ai][bj][m][n] = __builtin_amdgcn_mfma_f32_16x16x32_bf16(Bf[n][k], Af[m][k], acc[ai][bj][m][n], 0, 0, 0); \
;     __builtin_amdgcn_s_setprio(0); } while (0)
; template <int BMODE, class Epi, class TileFn>
; DEV void gemm_loop(LAS unsigned char* lds, const bf16_t* __restrict__ A, int lda, const bf16_t* __restrict__ B, int ldb, int K, const Epi& epi, int t0, int tstep, int tend, const TileFn& tf) {
;     ...
;         for (int t = 0; t < nt; t += 2) {
;             const bool last = (t == nt - 2);
;             const char* a1 = cA + (size_t)(t + 1) * 128;
;             const char* a2 = last ? nA : cA + (size_t)(t + 2) * 128;
;             const char* b2 = last ? nB : cB + (size_t)(t + 2) * bks;
;             const char* a3 = a2 + 128; const char* b3 = b2 + bks;
;             LDB(B0, 0, 0); LDB(B1, 0, 1); SCHED; LDA(At, 0, 0); STG_A(1, 1, a1);
;             WAIT_V(8); WAIT_L(0); BAR; MMA(0, 0, At, B0); MMA(0, 1, At, B1); BAR; SCHED;
;             LDA(At, 0, 1); STG_B(0, 0, b2); STG_B(0, 1, b2); STG_A(0, 0, a2);
;             WAIT_V(8); WAIT_L(0); BAR; MMA(1, 0, At, B0); MMA(1, 1, At, B1); BAR; SCHED;
	s_setprio 0
	v_mfma_f32_16x16x32_bf16 v[60:63], v[158:161], v[200:203], 0
	v_mfma_f32_16x16x32_bf16 v[56:59], v[166:169], v[200:203], 0
	v_mfma_f32_16x16x32_bf16 v[40:43], v[158:161], v[216:219], 0
	v_mfma_f32_16x16x32_bf16 v[44:47], v[166:169], v[216:219], 0
	v_mfma_f32_16x16x32_bf16 v[28:31], v[158:161], v[224:227], 0
	v_mfma_f32_16x16x32_bf16 v[24:27], v[166:169], v[224:227], 0
	v_mfma_f32_16x16x32_bf16 v[8:11], v[158:161], v[232:235], 0
	v_mfma_f32_16x16x32_bf16 v[12:15], v[166:169], v[232:235], 0
	v_mfma_f32_16x16x32_bf16 v[60:63], v[162:165], v[212:215], v[60:63]
	v_mfma_f32_16x16x32_bf16 v[56:59], v[170:173], v[212:215], v[56:59]
	v_mfma_f32_16x16x32_bf16 v[40:43], v[162:165], v[220:223], v[40:43]
	v_mfma_f32_16x16x32_bf16 v[44:47], v[170:173], v[220:223], v[44:47]
	v_mfma_f32_16x16x32_bf16 v[28:31], v[162:165], v[228:231], v[28:31]
	v_mfma_f32_16x16x32_bf16 v[24:27], v[170:173], v[228:231], v[24:27]
	v_mfma_f32_16x16x32_bf16 v[8:11], v[162:165], v[236:239], v[8:11]
	v_mfma_f32_16x16x32_bf16 v[12:15], v[170:173], v[236:239], v[12:15]
	v_mfma_f32_16x16x32_bf16 v[52:55], v[174:177], v[200:203], 0
	v_mfma_f32_16x16x32_bf16 v[48:51], v[182:185], v[200:203], 0
	v_mfma_f32_16x16x32_bf16 v[32:35], v[174:177], v[216:219], 0
	v_mfma_f32_16x16x32_bf16 v[36:39], v[182:185], v[216:219], 0
	v_mfma_f32_16x16x32_bf16 v[20:23], v[174:177], v[224:227], 0
	v_mfma_f32_16x16x32_bf16 v[16:19], v[182:185], v[224:227], 0
	v_mfma_f32_16x16x32_bf16 v[0:3], v[174:177], v[232:235], 0
	v_mfma_f32_16x16x32_bf16 v[4:7], v[182:185], v[232:235], 0
	v_mfma_f32_16x16x32_bf16 v[52:55], v[178:181], v[212:215], v[52:55]
	v_mfma_f32_16x16x32_bf16 v[48:51], v[196:199], v[212:215], v[48:51]
	v_mfma_f32_16x16x32_bf16 v[32:35], v[178:181], v[220:223], v[32:35]
	v_mfma_f32_16x16x32_bf16 v[36:39], v[196:199], v[220:223], v[36:39]
	v_mfma_f32_16x16x32_bf16 v[20:23], v[178:181], v[228:231], v[20:23]
	v_mfma_f32_16x16x32_bf16 v[16:19], v[196:199], v[228:231], v[16:19]
	v_mfma_f32_16x16x32_bf16 v[0:3], v[178:181], v[236:239], v[0:3]
	v_mfma_f32_16x16x32_bf16 v[4:7], v[196:199], v[236:239], v[4:7]
	s_barrier
	s_setprio 1
	s_branch .Lkmid_1338
.LBB0_1338:
	ds_read_b128 v[158:161], v156
	ds_read_b128 v[162:165], v156 offset:1024
	ds_read_b128 v[166:169], v156 offset:2048
	ds_read_b128 v[170:173], v156 offset:3072
	ds_read_b128 v[174:177], v156 offset:16384
	ds_read_b128 v[178:181], v156 offset:17408
	ds_read_b128 v[182:185], v156 offset:18432
	ds_read_b128 v[196:199], v156 offset:19456
	s_add_u32 s8, s75, s36
	s_addc_u32 s9, s81, s37
	s_add_u32 s8, s8, 0x62e6100
	s_addc_u32 s9, s9, 0
	s_add_u32 s31, s92, s36
	s_addc_u32 s95, s93, s37
	s_cmpk_eq_i32 s36, 0x700
	s_cselect_b32 s55, s50, s9
	s_cselect_b32 s54, s30, s8
	s_cselect_b32 s9, s74, s95
	s_cselect_b32 s8, s53, s31
	v_add_u32_e32 v194, 0xc000, v141
	v_lshl_add_u64 v[186:187], v[136:137], 0, s[36:37]
	v_readfirstlane_b32 s31, v194
	v_add_u32_e32 v194, 0xe000, v141
	s_mov_b32 m0, s31
	v_readfirstlane_b32 s31, v194
	ds_read_b128 v[200:203], v157
	ds_read_b128 v[212:215], v157 offset:1024
	ds_read_b128 v[216:219], v157 offset:2048
	ds_read_b128 v[220:223], v157 offset:3072
	ds_read_b128 v[224:227], v157 offset:4096
	ds_read_b128 v[228:231], v157 offset:5120
	ds_read_b128 v[232:235], v157 offset:6144
	ds_read_b128 v[236:239], v157 offset:7168
	global_load_lds_dwordx4 v[186:187], off
	v_lshl_add_u64 v[186:187], v[138:139], 0, s[36:37]
	s_mov_b32 m0, s31
	s_nop 0
	global_load_lds_dwordx4 v[186:187], off
	s_waitcnt vmcnt(8)
	s_waitcnt lgkmcnt(0)
	s_barrier
	s_setprio 0
	v_mfma_f32_16x16x32_bf16 v[124:127], v[158:161], v[200:203], v[124:127]
	v_mfma_f32_16x16x32_bf16 v[120:123], v[166:169], v[200:203], v[120:123]
	v_mfma_f32_16x16x32_bf16 v[104:107], v[158:161], v[216:219], v[104:107]
	v_mfma_f32_16x16x32_bf16 v[108:111], v[166:169], v[216:219], v[108:111]
	v_mfma_f32_16x16x32_bf16 v[92:95], v[158:161], v[224:227], v[92:95]
	v_mfma_f32_16x16x32_bf16 v[88:91], v[166:169], v[224:227], v[88:91]
	v_mfma_f32_16x16x32_bf16 v[72:75], v[158:161], v[232:235], v[72:75]
	v_mfma_f32_16x16x32_bf16 v[76:79], v[166:169], v[232:235], v[76:79]
	v_mfma_f32_16x16x32_bf16 v[124:127], v[162:165], v[212:215], v[124:127]
	v_mfma_f32_16x16x32_bf16 v[120:123], v[170:173], v[212:215], v[120:123]
	v_mfma_f32_16x16x32_bf16 v[104:107], v[162:165], v[220:223], v[104:107]
	v_mfma_f32_16x16x32_bf16 v[108:111], v[170:173], v[220:223], v[108:111]
	v_mfma_f32_16x16x32_bf16 v[92:95], v[162:165], v[228:231], v[92:95]
	v_mfma_f32_16x16x32_bf16 v[88:91], v[170:173], v[228:231], v[88:91]
	v_mfma_f32_16x16x32_bf16 v[72:75], v[162:165], v[236:239], v[72:75]
	v_mfma_f32_16x16x32_bf16 v[76:79], v[170:173], v[236:239], v[76:79]
	v_mfma_f32_16x16x32_bf16 v[116:119], v[174:177], v[200:203], v[116:119]
	v_mfma_f32_16x16x32_bf16 v[112:115], v[182:185], v[200:203], v[112:115]
	v_mfma_f32_16x16x32_bf16 v[96:99], v[174:177], v[216:219], v[96:99]
	v_mfma_f32_16x16x32_bf16 v[100:103], v[182:185], v[216:219], v[100:103]
	v_mfma_f32_16x16x32_bf16 v[84:87], v[174:177], v[224:227], v[84:87]
	v_mfma_f32_16x16x32_bf16 v[80:83], v[182:185], v[224:227], v[80:83]
	v_mfma_f32_16x16x32_bf16 v[64:67], v[174:177], v[232:235], v[64:67]
	v_mfma_f32_16x16x32_bf16 v[68:71], v[182:185], v[232:235], v[68:71]
	v_mfma_f32_16x16x32_bf16 v[116:119], v[178:181], v[212:215], v[116:119]
	v_mfma_f32_16x16x32_bf16 v[112:115], v[196:199], v[212:215], v[112:115]
	v_mfma_f32_16x16x32_bf16 v[96:99], v[178:181], v[220:223], v[96:99]
	v_mfma_f32_16x16x32_bf16 v[100:103], v[196:199], v[220:223], v[100:103]
	v_mfma_f32_16x16x32_bf16 v[84:87], v[178:181], v[228:231], v[84:87]
	v_mfma_f32_16x16x32_bf16 v[80:83], v[196:199], v[228:231], v[80:83]
	v_mfma_f32_16x16x32_bf16 v[64:67], v[178:181], v[236:239], v[64:67]
	v_mfma_f32_16x16x32_bf16 v[68:71], v[196:199], v[236:239], v[68:71]
	s_barrier
; #define WAIT_V(n) asm volatile("s_waitcnt vmcnt(" #n ")" ::: "memory")
; #define WAIT_L(n) asm volatile("s_waitcnt lgkmcnt(" #n ")" ::: "memory")
; #define BAR __builtin_amdgcn_s_barrier()
; #define SCHED __builtin_amdgcn_sched_barrier(0)
; #define STG_A(b, h, ptr) do { const char* _g = (ptr) + (h) * ahalf; LAS unsigned char* _l = lw + ((b) * 2 + (h)) * 16384; GLDS(_g + voa0, _l); GLDS(_g + voa1, _l + 8192); } while (0)
; #define STG_B(b, h, ptr) do { const char* _g = (ptr) + (h) * bhalf; LAS unsigned char* _l = lw + 65536 + ((b) * 2 + (h)) * 16384; GLDS(_g + vob0, _l); GLDS(_g + vob1, _l + 8192); } while (0)
; #define LDA(dst, b, h) _Pragma("unroll") for (int m = 0; m < 4; ++m) _Pragma("unroll") for (int k = 0; k < 2; ++k) dst[m][k] = *(const LAS bf16x8*)(la + ((b) * 2 + (h)) * 16384 + m * 2048 + k * 1024)
; #define LDB(dst, b, h) _Pragma("unroll") for (int n = 0; n < 2; ++n) _Pragma("unroll") for (int k = 0; k < 2; ++k) dst[n][k] = *(const LAS bf16x8*)(lb + ((b) * 2 + (h)) * 16384 + n * 2048 + k * 1024)
; #define MMA(ai, bj, Af, Bf) do { __builtin_amdgcn_s_setprio(1); \
;     _Pragma("unroll") for (int m = 0; m < 4; ++m) _Pragma("unroll") for (int n = 0; n < 2; ++n) _Pragma("unroll") for (int k = 0; k < 2; ++k) \
;         acc[ai][bj][m][n] = __builtin_amdgcn_mfma_f32_16x16x32_bf16(Bf[n][k], Af[m][k], acc[ai][bj][m][n], 0, 0, 0); \
;     __builtin_amdgcn_s_setprio(0); } while (0)
; template <int BMODE, class Epi, class TileFn>
; DEV void gemm_loop(LAS unsigned char* lds, const bf16_t* __restrict__ A, int lda, const bf16_t* __restrict__ B, int ldb, int K, const Epi& epi, int t0, int tstep, int tend, const TileFn& tf) {
;     ...
;             LDA(At, 0, 1); STG_B(0, 0, b2); STG_B(0, 1, b2); STG_A(0, 0, a2);
;             WAIT_V(8); WAIT_L(0); BAR; MMA(1, 0, At, B0); MMA(1, 1, At, B1); BAR; SCHED;
;             LDB(B0, 1, 0); LDB(B1, 1, 1); SCHED; LDA(At, 1, 0); STG_A(0, 1, a2);
;             WAIT_V(8); WAIT_L(0); BAR; MMA(0, 0, At, B0); MMA(0, 1, At, B1); BAR; SCHED;
	s_setprio 1
	v_readfirstlane_b32 s31, v142
	v_lshl_add_u64 v[186:187], s[8:9], 0, v[128:129]
	s_mov_b32 m0, s31
	v_readfirstlane_b32 s31, v143
	s_add_u32 s96, s8, 0x40000
	ds_read_b128 v[200:203], v157 offset:16384
	ds_read_b128 v[212:215], v157 offset:17408
	ds_read_b128 v[216:219], v157 offset:18432
	ds_read_b128 v[220:223], v157 offset:19456
	ds_read_b128 v[224:227], v157 offset:20480
	ds_read_b128 v[228:231], v157 offset:21504
	ds_read_b128 v[232:235], v157 offset:22528
	ds_read_b128 v[236:239], v157 offset:23552
	global_load_lds_dwordx4 v[186:187], off
	v_lshl_add_u64 v[204:205], s[8:9], 0, v[130:131]
	s_mov_b32 m0, s31
	s_addc_u32 s97, s9, 0
	v_readfirstlane_b32 s31, v144
	global_load_lds_dwordx4 v[204:205], off
	v_lshl_add_u64 v[240:241], s[96:97], 0, v[128:129]
	s_mov_b32 m0, s31
	v_readfirstlane_b32 s31, v145
	global_load_lds_dwordx4 v[240:241], off
	v_lshl_add_u64 v[240:241], s[96:97], 0, v[130:131]
	s_mov_b32 m0, s31
	v_readfirstlane_b32 s31, v141
	global_load_lds_dwordx4 v[240:241], off
	v_lshl_add_u64 v[240:241], s[54:55], 0, v[128:129]
	s_mov_b32 m0, s31
	v_readfirstlane_b32 s31, v146
	global_load_lds_dwordx4 v[240:241], off
	v_lshl_add_u64 v[242:243], s[54:55], 0, v[130:131]
	s_mov_b32 m0, s31
	s_nop 0
	global_load_lds_dwordx4 v[242:243], off
	s_waitcnt vmcnt(8)
	s_waitcnt lgkmcnt(0)
	s_barrier
	s_setprio 0
	v_mfma_f32_16x16x32_bf16 v[60:63], v[158:161], v[200:203], v[60:63]
	v_mfma_f32_16x16x32_bf16 v[56:59], v[166:169], v[200:203], v[56:59]
	v_mfma_f32_16x16x32_bf16 v[40:43], v[158:161], v[216:219], v[40:43]
	v_mfma_f32_16x16x32_bf16 v[44:47], v[166:169], v[216:219], v[44:47]
	v_mfma_f32_16x16x32_bf16 v[28:31], v[158:161], v[224:227], v[28:31]
	v_mfma_f32_16x16x32_bf16 v[24:27], v[166:169], v[224:227], v[24:27]
	v_mfma_f32_16x16x32_bf16 v[8:11], v[158:161], v[232:235], v[8:11]
	v_mfma_f32_16x16x32_bf16 v[12:15], v[166:169], v[232:235], v[12:15]
	v_mfma_f32_16x16x32_bf16 v[60:63], v[162:165], v[212:215], v[60:63]
	v_mfma_f32_16x16x32_bf16 v[56:59], v[170:173], v[212:215], v[56:59]
	v_mfma_f32_16x16x32_bf16 v[40:43], v[162:165], v[220:223], v[40:43]
	v_mfma_f32_16x16x32_bf16 v[44:47], v[170:173], v[220:223], v[44:47]
	v_mfma_f32_16x16x32_bf16 v[28:31], v[162:165], v[228:231], v[28:31]
	v_mfma_f32_16x16x32_bf16 v[24:27], v[170:173], v[228:231], v[24:27]
	v_mfma_f32_16x16x32_bf16 v[8:11], v[162:165], v[236:239], v[8:11]
	v_mfma_f32_16x16x32_bf16 v[12:15], v[170:173], v[236:239], v[12:15]
	v_mfma_f32_16x16x32_bf16 v[52:55], v[174:177], v[200:203], v[52:55]
	v_mfma_f32_16x16x32_bf16 v[48:51], v[182:185], v[200:203], v[48:51]
	v_mfma_f32_16x16x32_bf16 v[32:35], v[174:177], v[216:219], v[32:35]
	v_mfma_f32_16x16x32_bf16 v[36:39], v[182:185], v[216:219], v[36:39]
	v_mfma_f32_16x16x32_bf16 v[20:23], v[174:177], v[224:227], v[20:23]
	v_mfma_f32_16x16x32_bf16 v[16:19], v[182:185], v[224:227], v[16:19]
	v_mfma_f32_16x16x32_bf16 v[0:3], v[174:177], v[232:235], v[0:3]
	v_mfma_f32_16x16x32_bf16 v[4:7], v[182:185], v[232:235], v[4:7]
	v_mfma_f32_16x16x32_bf16 v[52:55], v[178:181], v[212:215], v[52:55]
	v_mfma_f32_16x16x32_bf16 v[48:51], v[196:199], v[212:215], v[48:51]
	v_mfma_f32_16x16x32_bf16 v[32:35], v[178:181], v[220:223], v[32:35]
	v_mfma_f32_16x16x32_bf16 v[36:39], v[196:199], v[220:223], v[36:39]
	v_mfma_f32_16x16x32_bf16 v[20:23], v[178:181], v[228:231], v[20:23]
	v_mfma_f32_16x16x32_bf16 v[16:19], v[196:199], v[228:231], v[16:19]
	v_mfma_f32_16x16x32_bf16 v[0:3], v[178:181], v[236:239], v[0:3]
	v_mfma_f32_16x16x32_bf16 v[4:7], v[196:199], v[236:239], v[4:7]
	s_barrier
	s_setprio 1
.Lkmid_1338:
	ds_read_b128 v[158:161], v156 offset:32768
	ds_read_b128 v[162:165], v156 offset:33792
	ds_read_b128 v[166:169], v156 offset:34816
	ds_read_b128 v[170:173], v156 offset:35840
	ds_read_b128 v[174:177], v156 offset:49152
	ds_read_b128 v[178:181], v156 offset:50176
	ds_read_b128 v[182:185], v156 offset:51200
	ds_read_b128 v[196:199], v156 offset:52224
	s_add_u32 s54, s54, 0x40000
	s_addc_u32 s55, s55, 0
	v_readfirstlane_b32 s31, v147
	v_lshl_add_u64 v[244:245], s[54:55], 0, v[128:129]
	s_mov_b32 m0, s31
	v_readfirstlane_b32 s31, v148
	ds_read_b128 v[200:203], v157 offset:32768
	ds_read_b128 v[212:215], v157 offset:33792
	ds_read_b128 v[216:219], v157 offset:34816
	ds_read_b128 v[220:223], v157 offset:35840
	ds_read_b128 v[224:227], v157 offset:36864
	ds_read_b128 v[228:231], v157 offset:37888
	ds_read_b128 v[232:235], v157 offset:38912
	ds_read_b128 v[236:239], v157 offset:39936
	global_load_lds_dwordx4 v[244:245], off
	v_lshl_add_u64 v[244:245], s[54:55], 0, v[130:131]
	s_mov_b32 m0, s31
	s_nop 0
	global_load_lds_dwordx4 v[244:245], off
	s_waitcnt vmcnt(8)
	s_waitcnt lgkmcnt(0)
	s_barrier
; #define WAIT_V(n) asm volatile("s_waitcnt vmcnt(" #n ")" ::: "memory")
; #define WAIT_L(n) asm volatile("s_waitcnt lgkmcnt(" #n ")" ::: "memory")
; #define BAR __builtin_amdgcn_s_barrier()
; #define SCHED __builtin_amdgcn_sched_barrier(0)
; #define STG_A(b, h, ptr) do { const char* _g = (ptr) + (h) * ahalf; LAS unsigned char* _l = lw + ((b) * 2 + (h)) * 16384; GLDS(_g + voa0, _l); GLDS(_g + voa1, _l + 8192); } while (0)
; #define STG_B(b, h, ptr) do { const char* _g = (ptr) + (h) * bhalf; LAS unsigned char* _l = lw + 65536 + ((b) * 2 + (h)) * 16384; GLDS(_g + vob0, _l); GLDS(_g + vob1, _l + 8192); } while (0)
; #define LDA(dst, b, h) _Pragma("unroll") for (int m = 0; m < 4; ++m) _Pragma("unroll") for (int k = 0; k < 2; ++k) dst[m][k] = *(const LAS bf16x8*)(la + ((b) * 2 + (h)) * 16384 + m * 2048 + k * 1024)
; #define MMA(ai, bj, Af, Bf) do { __builtin_amdgcn_s_setprio(1); \
;     _Pragma("unroll") for (int m = 0; m < 4; ++m) _Pragma("unroll") for (int n = 0; n < 2; ++n) _Pragma("unroll") for (int k = 0; k < 2; ++k) \
;         acc[ai][bj][m][n] = __builtin_amdgcn_mfma_f32_16x16x32_bf16(Bf[n][k], Af[m][k], acc[ai][bj][m][n], 0, 0, 0); \
;     __builtin_amdgcn_s_setprio(0); } while (0)
; template <int BMODE, class Epi, class TileFn>
; DEV void gemm_loop(LAS unsigned char* lds, const bf16_t* __restrict__ A, int lda, const bf16_t* __restrict__ B, int ldb, int K, const Epi& epi, int t0, int tstep, int tend, const TileFn& tf) {
;     ...
;             WAIT_V(8); WAIT_L(0); BAR; MMA(0, 0, At, B0); MMA(0, 1, At, B1); BAR; SCHED;
;             LDA(At, 1, 1); STG_B(1, 0, b3); STG_B(1, 1, b3); STG_A(1, 0, a3);
;             WAIT_V(8); WAIT_L(0); BAR; MMA(1, 0, At, B0); MMA(1, 1, At, B1); BAR; SCHED;
;         }
	s_setprio 0
	v_mfma_f32_16x16x32_bf16 v[124:127], v[158:161], v[200:203], v[124:127]
	v_mfma_f32_16x16x32_bf16 v[120:123], v[166:169], v[200:203], v[120:123]
	v_mfma_f32_16x16x32_bf16 v[104:107], v[158:161], v[216:219], v[104:107]
	v_mfma_f32_16x16x32_bf16 v[108:111], v[166:169], v[216:219], v[108:111]
	v_mfma_f32_16x16x32_bf16 v[92:95], v[158:161], v[224:227], v[92:95]
	v_mfma_f32_16x16x32_bf16 v[88:91], v[166:169], v[224:227], v[88:91]
	v_mfma_f32_16x16x32_bf16 v[72:75], v[158:161], v[232:235], v[72:75]
	v_mfma_f32_16x16x32_bf16 v[76:79], v[166:169], v[232:235], v[76:79]
	v_mfma_f32_16x16x32_bf16 v[124:127], v[162:165], v[212:215], v[124:127]
	v_mfma_f32_16x16x32_bf16 v[120:123], v[170:173], v[212:215], v[120:123]
	v_mfma_f32_16x16x32_bf16 v[104:107], v[162:165], v[220:223], v[104:107]
	v_mfma_f32_16x16x32_bf16 v[108:111], v[170:173], v[220:223], v[108:111]
	v_mfma_f32_16x16x32_bf16 v[92:95], v[162:165], v[228:231], v[92:95]
	v_mfma_f32_16x16x32_bf16 v[88:91], v[170:173], v[228:231], v[88:91]
	v_mfma_f32_16x16x32_bf16 v[72:75], v[162:165], v[236:239], v[72:75]
	v_mfma_f32_16x16x32_bf16 v[76:79], v[170:173], v[236:239], v[76:79]
	v_mfma_f32_16x16x32_bf16 v[116:119], v[174:177], v[200:203], v[116:119]
	v_mfma_f32_16x16x32_bf16 v[112:115], v[182:185], v[200:203], v[112:115]
	v_mfma_f32_16x16x32_bf16 v[96:99], v[174:177], v[216:219], v[96:99]
	v_mfma_f32_16x16x32_bf16 v[100:103], v[182:185], v[216:219], v[100:103]
	v_mfma_f32_16x16x32_bf16 v[84:87], v[174:177], v[224:227], v[84:87]
	v_mfma_f32_16x16x32_bf16 v[80:83], v[182:185], v[224:227], v[80:83]
	v_mfma_f32_16x16x32_bf16 v[64:67], v[174:177], v[232:235], v[64:67]
	v_mfma_f32_16x16x32_bf16 v[68:71], v[182:185], v[232:235], v[68:71]
	v_mfma_f32_16x16x32_bf16 v[116:119], v[178:181], v[212:215], v[116:119]
	v_mfma_f32_16x16x32_bf16 v[112:115], v[196:199], v[212:215], v[112:115]
	v_mfma_f32_16x16x32_bf16 v[96:99], v[178:181], v[220:223], v[96:99]
	v_mfma_f32_16x16x32_bf16 v[100:103], v[196:199], v[220:223], v[100:103]
	v_mfma_f32_16x16x32_bf16 v[84:87], v[178:181], v[228:231], v[84:87]
	v_mfma_f32_16x16x32_bf16 v[80:83], v[196:199], v[228:231], v[80:83]
	v_mfma_f32_16x16x32_bf16 v[64:67], v[178:181], v[236:239], v[64:67]
	v_mfma_f32_16x16x32_bf16 v[68:71], v[196:199], v[236:239], v[68:71]
	s_barrier
	s_setprio 1
	v_readfirstlane_b32 s31, v149
	v_lshl_add_u64 v[186:187], v[186:187], 0, s[2:3]
	s_mov_b32 m0, s31
	v_readfirstlane_b32 s31, v150
	s_add_u32 s8, s8, 0x40080
	ds_read_b128 v[200:203], v157 offset:49152
	ds_read_b128 v[212:215], v157 offset:50176
	ds_read_b128 v[216:219], v157 offset:51200
	ds_read_b128 v[220:223], v157 offset:52224
	ds_read_b128 v[224:227], v157 offset:53248
	ds_read_b128 v[228:231], v157 offset:54272
	ds_read_b128 v[232:235], v157 offset:55296
	ds_read_b128 v[236:239], v157 offset:56320
	global_load_lds_dwordx4 v[186:187], off
	v_lshl_add_u64 v[186:187], v[204:205], 0, s[2:3]
	s_mov_b32 m0, s31
	s_addc_u32 s9, s9, 0
	v_readfirstlane_b32 s31, v153
	global_load_lds_dwordx4 v[186:187], off
	v_lshl_add_u64 v[186:187], s[8:9], 0, v[128:129]
	s_mov_b32 m0, s31
	s_nop 0
	global_load_lds_dwordx4 v[186:187], off
	v_lshl_add_u64 v[186:187], s[8:9], 0, v[130:131]
	v_readfirstlane_b32 s8, v154
	s_mov_b32 m0, s8
	v_readfirstlane_b32 s8, v151
	global_load_lds_dwordx4 v[186:187], off
	v_lshl_add_u64 v[186:187], v[240:241], 0, s[2:3]
	s_mov_b32 m0, s8
	v_readfirstlane_b32 s8, v152
	global_load_lds_dwordx4 v[186:187], off
	v_lshl_add_u64 v[186:187], v[242:243], 0, s[2:3]
	s_mov_b32 m0, s8
	s_nop 0
	global_load_lds_dwordx4 v[186:187], off
	s_waitcnt vmcnt(8)
	s_waitcnt lgkmcnt(0)
	s_barrier
	s_setprio 0
	v_mfma_f32_16x16x32_bf16 v[60:63], v[158:161], v[200:203], v[60:63]
	v_mfma_f32_16x16x32_bf16 v[56:59], v[166:169], v[200:203], v[56:59]
	v_mfma_f32_16x16x32_bf16 v[40:43], v[158:161], v[216:219], v[40:43]
	v_mfma_f32_16x16x32_bf16 v[44:47], v[166:169], v[216:219], v[44:47]
	v_mfma_f32_16x16x32_bf16 v[28:31], v[158:161], v[224:227], v[28:31]
	v_mfma_f32_16x16x32_bf16 v[24:27], v[166:169], v[224:227], v[24:27]
	v_mfma_f32_16x16x32_bf16 v[8:11], v[158:161], v[232:235], v[8:11]
	v_mfma_f32_16x16x32_bf16 v[12:15], v[166:169], v[232:235], v[12:15]
	v_mfma_f32_16x16x32_bf16 v[60:63], v[162:165], v[212:215], v[60:63]
	v_mfma_f32_16x16x32_bf16 v[56:59], v[170:173], v[212:215], v[56:59]
	v_mfma_f32_16x16x32_bf16 v[40:43], v[162:165], v[220:223], v[40:43]
	v_mfma_f32_16x16x32_bf16 v[44:47], v[170:173], v[220:223], v[44:47]
	v_mfma_f32_16x16x32_bf16 v[28:31], v[162:165], v[228:231], v[28:31]
	v_mfma_f32_16x16x32_bf16 v[24:27], v[170:173], v[228:231], v[24:27]
	v_mfma_f32_16x16x32_bf16 v[8:11], v[162:165], v[236:239], v[8:11]
	v_mfma_f32_16x16x32_bf16 v[12:15], v[170:173], v[236:239], v[12:15]
	v_mfma_f32_16x16x32_bf16 v[52:55], v[174:177], v[200:203], v[52:55]
	v_mfma_f32_16x16x32_bf16 v[48:51], v[182:185], v[200:203], v[48:51]
	v_mfma_f32_16x16x32_bf16 v[32:35], v[174:177], v[216:219], v[32:35]
	v_mfma_f32_16x16x32_bf16 v[36:39], v[182:185], v[216:219], v[36:39]
	v_mfma_f32_16x16x32_bf16 v[20:23], v[174:177], v[224:227], v[20:23]
	v_mfma_f32_16x16x32_bf16 v[16:19], v[182:185], v[224:227], v[16:19]
	v_mfma_f32_16x16x32_bf16 v[0:3], v[174:177], v[232:235], v[0:3]
	v_mfma_f32_16x16x32_bf16 v[4:7], v[182:185], v[232:235], v[4:7]
	v_mfma_f32_16x16x32_bf16 v[52:55], v[178:181], v[212:215], v[52:55]
	v_mfma_f32_16x16x32_bf16 v[48:51], v[196:199], v[212:215], v[48:51]
	v_mfma_f32_16x16x32_bf16 v[32:35], v[178:181], v[220:223], v[32:35]
	v_mfma_f32_16x16x32_bf16 v[36:39], v[196:199], v[220:223], v[36:39]
	v_mfma_f32_16x16x32_bf16 v[20:23], v[178:181], v[228:231], v[20:23]
	v_mfma_f32_16x16x32_bf16 v[16:19], v[196:199], v[228:231], v[16:19]
	v_mfma_f32_16x16x32_bf16 v[0:3], v[178:181], v[236:239], v[0:3]
	v_mfma_f32_16x16x32_bf16 v[4:7], v[196:199], v[236:239], v[4:7]
	s_barrier
	s_setprio 1
	s_add_i32 s94, s94, 2
	s_add_u32 s36, s36, 0x100
	s_addc_u32 s37, s37, 0
	s_cmp_gt_u32 s94, 13
	s_cbranch_scc0 .LBB0_1338
	s_setprio 0
	s_and_saveexec_b64 s[8:9], s[44:45]
	s_cbranch_execz .LBB0_1341
	s_barrier

; #define WAIT_V(n) asm volatile("s_waitcnt vmcnt(" #n ")" ::: "memory")
; #define WAIT_L(n) asm volatile("s_waitcnt lgkmcnt(" #n ")" ::: "memory")
; #define BAR __builtin_amdgcn_s_barrier()
; #define SCHED __builtin_amdgcn_sched_barrier(0)
; #define STG_A(b, h, ptr) do { const char* _g = (ptr) + (h) * ahalf; LAS unsigned char* _l = lw + ((b) * 2 + (h)) * 16384; GLDS(_g + voa0, _l); GLDS(_g + voa1, _l + 8192); } while (0)
; #define STG_B(b, h, ptr) do { const char* _g = (ptr) + (h) * bhalf; LAS unsigned char* _l = lw + 65536 + ((b) * 2 + (h)) * 16384; GLDS(_g + vob0, _l); GLDS(_g + vob1, _l + 8192); } while (0)
; #define LDA(dst, b, h) _Pragma("unroll") for (int m = 0; m < 4; ++m) _Pragma("unroll") for (int k = 0; k < 2; ++k) dst[m][k] = *(const LAS bf16x8*)(la + ((b) * 2 + (h)) * 16384 + m * 2048 + k * 1024)
; #define LDB(dst, b, h) _Pragma("unroll") for (int n = 0; n < 2; ++n) _Pragma("unroll") for (int k = 0; k < 2; ++k) dst[n][k] = *(const LAS bf16x8*)(lb + ((b) * 2 + (h)) * 16384 + n * 2048 + k * 1024)
; template <int BMODE, class Epi, class TileFn>
; DEV void gemm_loop(LAS unsigned char* lds, const bf16_t* __restrict__ A, int lda, const bf16_t* __restrict__ B, int ldb, int K, const Epi& epi, int t0, int tstep, int tend, const TileFn& tf) {
;     ...
;     for (int tt = t0;; tt += tstep, par ^= 1) {
;         const bool has_next = tt + tstep < tend;
;         epi.prefetch(lds, brow, par, tid);
;         int nrow = brow, ncol = bcol;
;         if (has_next) tf(tt + tstep, nrow, ncol);
;         const char* nA = (const char*)(A + (size_t)nrow * lda);
;         const char* nB = BMODE == 0 ? (const char*)(B + (size_t)ncol * ldb) : (const char*)(B + (size_t)ncol * 8);
;         for (int t = 0; t < nt; t += 2) {
;             const bool last = (t == nt - 2);
;             const char* a1 = cA + (size_t)(t + 1) * 128;
;             const char* a2 = last ? nA : cA + (size_t)(t + 2) * 128;
;             const char* b2 = last ? nB : cB + (size_t)(t + 2) * bks;
;             const char* a3 = a2 + 128; const char* b3 = b2 + bks;
;             LDB(B0, 0, 0); LDB(B1, 0, 1); SCHED; LDA(At, 0, 0); STG_A(1, 1, a1);
;             WAIT_V(8); WAIT_L(0); BAR; MMA(0, 0, At, B0); MMA(0, 1, At, B1); BAR; SCHED;
;             LDA(At, 0, 1); STG_B(0, 0, b2); STG_B(0, 1, b2); STG_A(0, 0, a2);
;             WAIT_V(8); WAIT_L(0); BAR; MMA(1, 0, At, B0); MMA(1, 1, At, B1); BAR; SCHED;
.LBB0_1440:
	s_mul_i32 s46, s7, 0x1600
	s_mul_hi_i32 s47, s7, 0x1600
	s_add_u32 s30, s70, s46
	s_addc_u32 s37, s71, s47
	s_mul_i32 s48, s28, 0x1600
	s_mul_hi_i32 s49, s28, 0x1600
	s_add_u32 s50, s42, s48
	s_addc_u32 s54, s43, s49
	s_add_u32 s55, s66, s8
	s_addc_u32 s74, s67, s9
	v_lshl_add_u64 v[120:121], v[200:201], 0, s[8:9]
	v_lshl_add_u64 v[122:123], v[202:203], 0, s[8:9]
	v_readlane_b32 s8, v250, 4
	s_add_u32 s75, s8, s0
	v_readlane_b32 s0, v250, 5
	s_addc_u32 s76, s0, s1
	s_mov_b32 s77, -2
	s_mov_b64 s[0:1], 0
	s_setprio 1
	ds_read_b128 v[132:135], v225
	ds_read_b128 v[136:139], v225 offset:1024
	ds_read_b128 v[140:143], v225 offset:2048
	ds_read_b128 v[144:147], v225 offset:3072
	ds_read_b128 v[148:151], v225 offset:16384
	ds_read_b128 v[152:155], v225 offset:17408
	ds_read_b128 v[156:159], v225 offset:18432
	ds_read_b128 v[160:163], v225 offset:19456
	s_add_u32 s8, s55, s0
	s_addc_u32 s9, s74, s1
	s_add_u32 s8, s8, 0xc366100
	s_addc_u32 s9, s9, 0
	s_add_u32 s31, s75, s0
	s_addc_u32 s80, s76, s1
	s_cmpk_eq_i32 s0, 0x1500
	s_cselect_b32 s53, s37, s9
	s_cselect_b32 s52, s30, s8
	s_cselect_b32 s9, s54, s80
	s_cselect_b32 s8, s50, s31
	v_add_u32_e32 v194, 0xc000, v211
	v_lshl_add_u64 v[204:205], v[120:121], 0, s[0:1]
	v_readfirstlane_b32 s31, v194
	v_add_u32_e32 v194, 0xe000, v211
	s_mov_b32 m0, s31
	v_readfirstlane_b32 s31, v194
	ds_read_b128 v[164:167], v226
	ds_read_b128 v[168:171], v226 offset:1024
	ds_read_b128 v[172:175], v226 offset:2048
	ds_read_b128 v[176:179], v226 offset:3072
	ds_read_b128 v[180:183], v226 offset:4096
	ds_read_b128 v[228:231], v226 offset:5120
	ds_read_b128 v[232:235], v226 offset:6144
	ds_read_b128 v[236:239], v226 offset:7168
	global_load_lds_dwordx4 v[204:205], off
	v_lshl_add_u64 v[204:205], v[122:123], 0, s[0:1]
	s_mov_b32 m0, s31
	s_nop 0
	global_load_lds_dwordx4 v[204:205], off
	s_waitcnt vmcnt(8)
	s_waitcnt lgkmcnt(0)
	s_barrier
	s_setprio 0
	v_mfma_f32_16x16x32_bf16 v[128:131], v[132:135], v[164:167], 0
	v_mfma_f32_16x16x32_bf16 v[124:127], v[140:143], v[164:167], 0
	v_mfma_f32_16x16x32_bf16 v[108:111], v[132:135], v[172:175], 0
	v_mfma_f32_16x16x32_bf16 v[104:107], v[140:143], v[172:175], 0
	v_mfma_f32_16x16x32_bf16 v[92:95], v[132:135], v[180:183], 0
	v_mfma_f32_16x16x32_bf16 v[88:91], v[140:143], v[180:183], 0
	v_mfma_f32_16x16x32_bf16 v[76:79], v[132:135], v[232:235], 0
	v_mfma_f32_16x16x32_bf16 v[72:75], v[140:143], v[232:235], 0
	v_mfma_f32_16x16x32_bf16 v[128:131], v[136:139], v[168:171], v[128:131]
	v_mfma_f32_16x16x32_bf16 v[124:127], v[144:147], v[168:171], v[124:127]
	v_mfma_f32_16x16x32_bf16 v[108:111], v[136:139], v[176:179], v[108:111]
	v_mfma_f32_16x16x32_bf16 v[104:107], v[144:147], v[176:179], v[104:107]
	v_mfma_f32_16x16x32_bf16 v[92:95], v[136:139], v[228:231], v[92:95]
	v_mfma_f32_16x16x32_bf16 v[88:91], v[144:147], v[228:231], v[88:91]
	v_mfma_f32_16x16x32_bf16 v[76:79], v[136:139], v[236:239], v[76:79]
	v_mfma_f32_16x16x32_bf16 v[72:75], v[144:147], v[236:239], v[72:75]
	v_mfma_f32_16x16x32_bf16 v[116:119], v[148:151], v[164:167], 0
	v_mfma_f32_16x16x32_bf16 v[112:115], v[156:159], v[164:167], 0
	v_mfma_f32_16x16x32_bf16 v[100:103], v[148:151], v[172:175], 0
	v_mfma_f32_16x16x32_bf16 v[96:99], v[156:159], v[172:175], 0
	v_mfma_f32_16x16x32_bf16 v[84:87], v[148:151], v[180:183], 0
	v_mfma_f32_16x16x32_bf16 v[80:83], v[156:159], v[180:183], 0
	v_mfma_f32_16x16x32_bf16 v[68:71], v[148:151], v[232:235], 0
	v_mfma_f32_16x16x32_bf16 v[64:67], v[156:159], v[232:235], 0
	v_mfma_f32_16x16x32_bf16 v[116:119], v[152:155], v[168:171], v[116:119]
	v_mfma_f32_16x16x32_bf16 v[112:115], v[160:163], v[168:171], v[112:115]
	v_mfma_f32_16x16x32_bf16 v[100:103], v[152:155], v[176:179], v[100:103]
	v_mfma_f32_16x16x32_bf16 v[96:99], v[160:163], v[176:179], v[96:99]
	v_mfma_f32_16x16x32_bf16 v[84:87], v[152:155], v[228:231], v[84:87]
	v_mfma_f32_16x16x32_bf16 v[80:83], v[160:163], v[228:231], v[80:83]
	v_mfma_f32_16x16x32_bf16 v[68:71], v[152:155], v[236:239], v[68:71]
	v_mfma_f32_16x16x32_bf16 v[64:67], v[160:163], v[236:239], v[64:67]
	s_barrier
	s_setprio 1
	v_readfirstlane_b32 s31, v212
	v_lshl_add_u64 v[204:205], s[8:9], 0, v[196:197]
	s_mov_b32 m0, s31
	v_readfirstlane_b32 s31, v213
	s_add_u32 s80, s8, 0xb0000
	ds_read_b128 v[164:167], v226 offset:16384
	ds_read_b128 v[168:171], v226 offset:17408
	ds_read_b128 v[172:175], v226 offset:18432
	ds_read_b128 v[176:179], v226 offset:19456
	ds_read_b128 v[180:183], v226 offset:20480
	ds_read_b128 v[228:231], v226 offset:21504
	ds_read_b128 v[232:235], v226 offset:22528
	ds_read_b128 v[236:239], v226 offset:23552
	global_load_lds_dwordx4 v[204:205], off
	v_lshl_add_u64 v[240:241], s[8:9], 0, v[198:199]
	s_mov_b32 m0, s31
	s_addc_u32 s81, s9, 0
	v_readfirstlane_b32 s31, v214
	global_load_lds_dwordx4 v[240:241], off
	v_lshl_add_u64 v[242:243], s[80:81], 0, v[196:197]
	s_mov_b32 m0, s31
	v_readfirstlane_b32 s31, v215
	global_load_lds_dwordx4 v[242:243], off
	v_lshl_add_u64 v[242:243], s[80:81], 0, v[198:199]
	s_mov_b32 m0, s31
	v_readfirstlane_b32 s31, v211
	global_load_lds_dwordx4 v[242:243], off
	v_lshl_add_u64 v[242:243], s[52:53], 0, v[184:185]
	s_mov_b32 m0, s31
	v_readfirstlane_b32 s31, v216
	global_load_lds_dwordx4 v[242:243], off
	v_lshl_add_u64 v[244:245], s[52:53], 0, v[186:187]
	s_mov_b32 m0, s31
	s_nop 0
	global_load_lds_dwordx4 v[244:245], off
	s_waitcnt vmcnt(8)
	s_waitcnt lgkmcnt(0)
	s_barrier
; #define WAIT_V(n) asm volatile("s_waitcnt vmcnt(" #n ")" ::: "memory")
; #define WAIT_L(n) asm volatile("s_waitcnt lgkmcnt(" #n ")" ::: "memory")
; #define BAR __builtin_amdgcn_s_barrier()
; #define SCHED __builtin_amdgcn_sched_barrier(0)
; #define STG_A(b, h, ptr) do { const char* _g = (ptr) + (h) * ahalf; LAS unsigned char* _l = lw + ((b) * 2 + (h)) * 16384; GLDS(_g + voa0, _l); GLDS(_g + voa1, _l + 8192); } while (0)
; #define STG_B(b, h, ptr) do { const char* _g = (ptr) + (h) * bhalf; LAS unsigned char* _l = lw + 65536 + ((b) * 2 + (h)) * 16384; GLDS(_g + vob0, _l); GLDS(_g + vob1, _l + 8192); } while (0)
; #define LDA(dst, b, h) _Pragma("unroll") for (int m = 0; m < 4; ++m) _Pragma("unroll") for (int k = 0; k < 2; ++k) dst[m][k] = *(const LAS bf16x8*)(la + ((b) * 2 + (h)) * 16384 + m * 2048 + k * 1024)
; #define LDB(dst, b, h) _Pragma("unroll") for (int n = 0; n < 2; ++n) _Pragma("unroll") for (int k = 0; k < 2; ++k) dst[n][k] = *(const LAS bf16x8*)(lb + ((b) * 2 + (h)) * 16384 + n * 2048 + k * 1024)
; #define MMA(ai, bj, Af, Bf) do { __builtin_amdgcn_s_setprio(1); \
;     _Pragma("unroll") for (int m = 0; m < 4; ++m) _Pragma("unroll") for (int n = 0; n < 2; ++n) _Pragma("unroll") for (int k = 0; k < 2; ++k) \
;         acc[ai][bj][m][n] = __builtin_amdgcn_mfma_f32_16x16x32_bf16(Bf[n][k], Af[m][k], acc[ai][bj][m][n], 0, 0, 0); \
;     __builtin_amdgcn_s_setprio(0); } while (0)
; template <int BMODE, class Epi, class TileFn>
; DEV void gemm_loop(LAS unsigned char* lds, const bf16_t* __restrict__ A, int lda, const bf16_t* __restrict__ B, int ldb, int K, const Epi& epi, int t0, int tstep, int tend, const TileFn& tf) {
;     ...
;         for (int t = 0; t < nt; t += 2) {
;             const bool last = (t == nt - 2);
;             const char* a1 = cA + (size_t)(t + 1) * 128;
;             const char* a2 = last ? nA : cA + (size_t)(t + 2) * 128;
;             const char* b2 = last ? nB : cB + (size_t)(t + 2) * bks;
;             const char* a3 = a2 + 128; const char* b3 = b2 + bks;
;             LDB(B0, 0, 0); LDB(B1, 0, 1); SCHED; LDA(At, 0, 0); STG_A(1, 1, a1);
;             WAIT_V(8); WAIT_L(0); BAR; MMA(0, 0, At, B0); MMA(0, 1, At, B1); BAR; SCHED;
;             LDA(At, 0, 1); STG_B(0, 0, b2); STG_B(0, 1, b2); STG_A(0, 0, a2);
;             WAIT_V(8); WAIT_L(0); BAR; MMA(1, 0, At, B0); MMA(1, 1, At, B1); BAR; SCHED;
	s_setprio 0
	v_mfma_f32_16x16x32_bf16 v[60:63], v[132:135], v[164:167], 0
	v_mfma_f32_16x16x32_bf16 v[56:59], v[140:143], v[164:167], 0
	v_mfma_f32_16x16x32_bf16 v[44:47], v[132:135], v[172:175], 0
	v_mfma_f32_16x16x32_bf16 v[40:43], v[140:143], v[172:175], 0
	v_mfma_f32_16x16x32_bf16 v[28:31], v[132:135], v[180:183], 0
	v_mfma_f32_16x16x32_bf16 v[24:27], v[140:143], v[180:183], 0
	v_mfma_f32_16x16x32_bf16 v[12:15], v[132:135], v[232:235], 0
	v_mfma_f32_16x16x32_bf16 v[8:11], v[140:143], v[232:235], 0
	v_mfma_f32_16x16x32_bf16 v[60:63], v[136:139], v[168:171], v[60:63]
	v_mfma_f32_16x16x32_bf16 v[56:59], v[144:147], v[168:171], v[56:59]
	v_mfma_f32_16x16x32_bf16 v[44:47], v[136:139], v[176:179], v[44:47]
	v_mfma_f32_16x16x32_bf16 v[40:43], v[144:147], v[176:179], v[40:43]
	v_mfma_f32_16x16x32_bf16 v[28:31], v[136:139], v[228:231], v[28:31]
	v_mfma_f32_16x16x32_bf16 v[24:27], v[144:147], v[228:231], v[24:27]
	v_mfma_f32_16x16x32_bf16 v[12:15], v[136:139], v[236:239], v[12:15]
	v_mfma_f32_16x16x32_bf16 v[8:11], v[144:147], v[236:239], v[8:11]
	v_mfma_f32_16x16x32_bf16 v[52:55], v[148:151], v[164:167], 0
	v_mfma_f32_16x16x32_bf16 v[48:51], v[156:159], v[164:167], 0
	v_mfma_f32_16x16x32_bf16 v[36:39], v[148:151], v[172:175], 0
	v_mfma_f32_16x16x32_bf16 v[32:35], v[156:159], v[172:175], 0
	v_mfma_f32_16x16x32_bf16 v[20:23], v[148:151], v[180:183], 0
	v_mfma_f32_16x16x32_bf16 v[16:19], v[156:159], v[180:183], 0
	v_mfma_f32_16x16x32_bf16 v[4:7], v[148:151], v[232:235], 0
	v_mfma_f32_16x16x32_bf16 v[0:3], v[156:159], v[232:235], 0
	v_mfma_f32_16x16x32_bf16 v[52:55], v[152:155], v[168:171], v[52:55]
	v_mfma_f32_16x16x32_bf16 v[48:51], v[160:163], v[168:171], v[48:51]
	v_mfma_f32_16x16x32_bf16 v[36:39], v[152:155], v[176:179], v[36:39]
	v_mfma_f32_16x16x32_bf16 v[32:35], v[160:163], v[176:179], v[32:35]
	v_mfma_f32_16x16x32_bf16 v[20:23], v[152:155], v[228:231], v[20:23]
	v_mfma_f32_16x16x32_bf16 v[16:19], v[160:163], v[228:231], v[16:19]
	v_mfma_f32_16x16x32_bf16 v[4:7], v[152:155], v[236:239], v[4:7]
	v_mfma_f32_16x16x32_bf16 v[0:3], v[160:163], v[236:239], v[0:3]
	s_barrier
	s_setprio 1
	s_branch .Lkmid_1441
.LBB0_1441:
	ds_read_b128 v[132:135], v225
	ds_read_b128 v[136:139], v225 offset:1024
	ds_read_b128 v[140:143], v225 offset:2048
	ds_read_b128 v[144:147], v225 offset:3072
	ds_read_b128 v[148:151], v225 offset:16384
	ds_read_b128 v[152:155], v225 offset:17408
	ds_read_b128 v[156:159], v225 offset:18432
	ds_read_b128 v[160:163], v225 offset:19456
	s_add_u32 s8, s55, s0
	s_addc_u32 s9, s74, s1
	s_add_u32 s8, s8, 0xc366100
	s_addc_u32 s9, s9, 0
	s_add_u32 s31, s75, s0
	s_addc_u32 s80, s76, s1
	s_cmpk_eq_i32 s0, 0x1500
	s_cselect_b32 s53, s37, s9
	s_cselect_b32 s52, s30, s8
	s_cselect_b32 s9, s54, s80
	s_cselect_b32 s8, s50, s31
	v_add_u32_e32 v194, 0xc000, v211
	v_lshl_add_u64 v[204:205], v[120:121], 0, s[0:1]
	v_readfirstlane_b32 s31, v194
	v_add_u32_e32 v194, 0xe000, v211
	s_mov_b32 m0, s31
	v_readfirstlane_b32 s31, v194
	ds_read_b128 v[164:167], v226
	ds_read_b128 v[168:171], v226 offset:1024
	ds_read_b128 v[172:175], v226 offset:2048
	ds_read_b128 v[176:179], v226 offset:3072
	ds_read_b128 v[180:183], v226 offset:4096
	ds_read_b128 v[228:231], v226 offset:5120
	ds_read_b128 v[232:235], v226 offset:6144
	ds_read_b128 v[236:239], v226 offset:7168
	global_load_lds_dwordx4 v[204:205], off
	v_lshl_add_u64 v[204:205], v[122:123], 0, s[0:1]
	s_mov_b32 m0, s31
	s_nop 0
	global_load_lds_dwordx4 v[204:205], off
	s_waitcnt vmcnt(8)
	s_waitcnt lgkmcnt(0)
	s_barrier
	s_setprio 0
	v_mfma_f32_16x16x32_bf16 v[128:131], v[132:135], v[164:167], v[128:131]
	v_mfma_f32_16x16x32_bf16 v[124:127], v[140:143], v[164:167], v[124:127]
	v_mfma_f32_16x16x32_bf16 v[108:111], v[132:135], v[172:175], v[108:111]
	v_mfma_f32_16x16x32_bf16 v[104:107], v[140:143], v[172:175], v[104:107]
	v_mfma_f32_16x16x32_bf16 v[92:95], v[132:135], v[180:183], v[92:95]
	v_mfma_f32_16x16x32_bf16 v[88:91], v[140:143], v[180:183], v[88:91]
	v_mfma_f32_16x16x32_bf16 v[76:79], v[132:135], v[232:235], v[76:79]
	v_mfma_f32_16x16x32_bf16 v[72:75], v[140:143], v[232:235], v[72:75]
	v_mfma_f32_16x16x32_bf16 v[128:131], v[136:139], v[168:171], v[128:131]
	v_mfma_f32_16x16x32_bf16 v[124:127], v[144:147], v[168:171], v[124:127]
	v_mfma_f32_16x16x32_bf16 v[108:111], v[136:139], v[176:179], v[108:111]
	v_mfma_f32_16x16x32_bf16 v[104:107], v[144:147], v[176:179], v[104:107]
	v_mfma_f32_16x16x32_bf16 v[92:95], v[136:139], v[228:231], v[92:95]
	v_mfma_f32_16x16x32_bf16 v[88:91], v[144:147], v[228:231], v[88:91]
	v_mfma_f32_16x16x32_bf16 v[76:79], v[136:139], v[236:239], v[76:79]
	v_mfma_f32_16x16x32_bf16 v[72:75], v[144:147], v[236:239], v[72:75]
	v_mfma_f32_16x16x32_bf16 v[116:119], v[148:151], v[164:167], v[116:119]
	v_mfma_f32_16x16x32_bf16 v[112:115], v[156:159], v[164:167], v[112:115]
	v_mfma_f32_16x16x32_bf16 v[100:103], v[148:151], v[172:175], v[100:103]
	v_mfma_f32_16x16x32_bf16 v[96:99], v[156:159], v[172:175], v[96:99]
	v_mfma_f32_16x16x32_bf16 v[84:87], v[148:151], v[180:183], v[84:87]
	v_mfma_f32_16x16x32_bf16 v[80:83], v[156:159], v[180:183], v[80:83]
	v_mfma_f32_16x16x32_bf16 v[68:71], v[148:151], v[232:235], v[68:71]
	v_mfma_f32_16x16x32_bf16 v[64:67], v[156:159], v[232:235], v[64:67]
	v_mfma_f32_16x16x32_bf16 v[116:119], v[152:155], v[168:171], v[116:119]
	v_mfma_f32_16x16x32_bf16 v[112:115], v[160:163], v[168:171], v[112:115]
	v_mfma_f32_16x16x32_bf16 v[100:103], v[152:155], v[176:179], v[100:103]
	v_mfma_f32_16x16x32_bf16 v[96:99], v[160:163], v[176:179], v[96:99]
	v_mfma_f32_16x16x32_bf16 v[84:87], v[152:155], v[228:231], v[84:87]
	v_mfma_f32_16x16x32_bf16 v[80:83], v[160:163], v[228:231], v[80:83]
	v_mfma_f32_16x16x32_bf16 v[68:71], v[152:155], v[236:239], v[68:71]
	v_mfma_f32_16x16x32_bf16 v[64:67], v[160:163], v[236:239], v[64:67]
	s_barrier
; #define WAIT_V(n) asm volatile("s_waitcnt vmcnt(" #n ")" ::: "memory")
; #define WAIT_L(n) asm volatile("s_waitcnt lgkmcnt(" #n ")" ::: "memory")
; #define BAR __builtin_amdgcn_s_barrier()
; #define SCHED __builtin_amdgcn_sched_barrier(0)
; #define STG_A(b, h, ptr) do { const char* _g = (ptr) + (h) * ahalf; LAS unsigned char* _l = lw + ((b) * 2 + (h)) * 16384; GLDS(_g + voa0, _l); GLDS(_g + voa1, _l + 8192); } while (0)
; #define STG_B(b, h, ptr) do { const char* _g = (ptr) + (h) * bhalf; LAS unsigned char* _l = lw + 65536 + ((b) * 2 + (h)) * 16384; GLDS(_g + vob0, _l); GLDS(_g + vob1, _l + 8192); } while (0)
; #define LDA(dst, b, h) _Pragma("unroll") for (int m = 0; m < 4; ++m) _Pragma("unroll") for (int k = 0; k < 2; ++k) dst[m][k] = *(const LAS bf16x8*)(la + ((b) * 2 + (h)) * 16384 + m * 2048 + k * 1024)
; #define LDB(dst, b, h) _Pragma("unroll") for (int n = 0; n < 2; ++n) _Pragma("unroll") for (int k = 0; k < 2; ++k) dst[n][k] = *(const LAS bf16x8*)(lb + ((b) * 2 + (h)) * 16384 + n * 2048 + k * 1024)
; #define MMA(ai, bj, Af, Bf) do { __builtin_amdgcn_s_setprio(1); \
;     _Pragma("unroll") for (int m = 0; m < 4; ++m) _Pragma("unroll") for (int n = 0; n < 2; ++n) _Pragma("unroll") for (int k = 0; k < 2; ++k) \
;         acc[ai][bj][m][n] = __builtin_amdgcn_mfma_f32_16x16x32_bf16(Bf[n][k], Af[m][k], acc[ai][bj][m][n], 0, 0, 0); \
;     __builtin_amdgcn_s_setprio(0); } while (0)
; template <int BMODE, class Epi, class TileFn>
; DEV void gemm_loop(LAS unsigned char* lds, const bf16_t* __restrict__ A, int lda, const bf16_t* __restrict__ B, int ldb, int K, const Epi& epi, int t0, int tstep, int tend, const TileFn& tf) {
;     ...
;             LDA(At, 0, 1); STG_B(0, 0, b2); STG_B(0, 1, b2); STG_A(0, 0, a2);
;             WAIT_V(8); WAIT_L(0); BAR; MMA(1, 0, At, B0); MMA(1, 1, At, B1); BAR; SCHED;
;             LDB(B0, 1, 0); LDB(B1, 1, 1); SCHED; LDA(At, 1, 0); STG_A(0, 1, a2);
;             WAIT_V(8); WAIT_L(0); BAR; MMA(0, 0, At, B0); MMA(0, 1, At, B1); BAR; SCHED;
	s_setprio 1
	v_readfirstlane_b32 s31, v212
	v_lshl_add_u64 v[204:205], s[8:9], 0, v[196:197]
	s_mov_b32 m0, s31
	v_readfirstlane_b32 s31, v213
	s_add_u32 s80, s8, 0xb0000
	ds_read_b128 v[164:167], v226 offset:16384
	ds_read_b128 v[168:171], v226 offset:17408
	ds_read_b128 v[172:175], v226 offset:18432
	ds_read_b128 v[176:179], v226 offset:19456
	ds_read_b128 v[180:183], v226 offset:20480
	ds_read_b128 v[228:231], v226 offset:21504
	ds_read_b128 v[232:235], v226 offset:22528
	ds_read_b128 v[236:239], v226 offset:23552
	global_load_lds_dwordx4 v[204:205], off
	v_lshl_add_u64 v[240:241], s[8:9], 0, v[198:199]
	s_mov_b32 m0, s31
	s_addc_u32 s81, s9, 0
	v_readfirstlane_b32 s31, v214
	global_load_lds_dwordx4 v[240:241], off
	v_lshl_add_u64 v[242:243], s[80:81], 0, v[196:197]
	s_mov_b32 m0, s31
	v_readfirstlane_b32 s31, v215
	global_load_lds_dwordx4 v[242:243], off
	v_lshl_add_u64 v[242:243], s[80:81], 0, v[198:199]
	s_mov_b32 m0, s31
	v_readfirstlane_b32 s31, v211
	global_load_lds_dwordx4 v[242:243], off
	v_lshl_add_u64 v[242:243], s[52:53], 0, v[184:185]
	s_mov_b32 m0, s31
	v_readfirstlane_b32 s31, v216
	global_load_lds_dwordx4 v[242:243], off
	v_lshl_add_u64 v[244:245], s[52:53], 0, v[186:187]
	s_mov_b32 m0, s31
	s_nop 0
	global_load_lds_dwordx4 v[244:245], off
	s_waitcnt vmcnt(8)
	s_waitcnt lgkmcnt(0)
	s_barrier
	s_setprio 0
	v_mfma_f32_16x16x32_bf16 v[60:63], v[132:135], v[164:167], v[60:63]
	v_mfma_f32_16x16x32_bf16 v[56:59], v[140:143], v[164:167], v[56:59]
	v_mfma_f32_16x16x32_bf16 v[44:47], v[132:135], v[172:175], v[44:47]
	v_mfma_f32_16x16x32_bf16 v[40:43], v[140:143], v[172:175], v[40:43]
	v_mfma_f32_16x16x32_bf16 v[28:31], v[132:135], v[180:183], v[28:31]
	v_mfma_f32_16x16x32_bf16 v[24:27], v[140:143], v[180:183], v[24:27]
	v_mfma_f32_16x16x32_bf16 v[12:15], v[132:135], v[232:235], v[12:15]
	v_mfma_f32_16x16x32_bf16 v[8:11], v[140:143], v[232:235], v[8:11]
	v_mfma_f32_16x16x32_bf16 v[60:63], v[136:139], v[168:171], v[60:63]
	v_mfma_f32_16x16x32_bf16 v[56:59], v[144:147], v[168:171], v[56:59]
	v_mfma_f32_16x16x32_bf16 v[44:47], v[136:139], v[176:179], v[44:47]
	v_mfma_f32_16x16x32_bf16 v[40:43], v[144:147], v[176:179], v[40:43]
	v_mfma_f32_16x16x32_bf16 v[28:31], v[136:139], v[228:231], v[28:31]
	v_mfma_f32_16x16x32_bf16 v[24:27], v[144:147], v[228:231], v[24:27]
	v_mfma_f32_16x16x32_bf16 v[12:15], v[136:139], v[236:239], v[12:15]
	v_mfma_f32_16x16x32_bf16 v[8:11], v[144:147], v[236:239], v[8:11]
	v_mfma_f32_16x16x32_bf16 v[52:55], v[148:151], v[164:167], v[52:55]
	v_mfma_f32_16x16x32_bf16 v[48:51], v[156:159], v[164:167], v[48:51]
	v_mfma_f32_16x16x32_bf16 v[36:39], v[148:151], v[172:175], v[36:39]
	v_mfma_f32_16x16x32_bf16 v[32:35], v[156:159], v[172:175], v[32:35]
	v_mfma_f32_16x16x32_bf16 v[20:23], v[148:151], v[180:183], v[20:23]
	v_mfma_f32_16x16x32_bf16 v[16:19], v[156:159], v[180:183], v[16:19]
	v_mfma_f32_16x16x32_bf16 v[4:7], v[148:151], v[232:235], v[4:7]
	v_mfma_f32_16x16x32_bf16 v[0:3], v[156:159], v[232:235], v[0:3]
	v_mfma_f32_16x16x32_bf16 v[52:55], v[152:155], v[168:171], v[52:55]
	v_mfma_f32_16x16x32_bf16 v[48:51], v[160:163], v[168:171], v[48:51]
	v_mfma_f32_16x16x32_bf16 v[36:39], v[152:155], v[176:179], v[36:39]
	v_mfma_f32_16x16x32_bf16 v[32:35], v[160:163], v[176:179], v[32:35]
	v_mfma_f32_16x16x32_bf16 v[20:23], v[152:155], v[228:231], v[20:23]
	v_mfma_f32_16x16x32_bf16 v[16:19], v[160:163], v[228:231], v[16:19]
	v_mfma_f32_16x16x32_bf16 v[4:7], v[152:155], v[236:239], v[4:7]
	v_mfma_f32_16x16x32_bf16 v[0:3], v[160:163], v[236:239], v[0:3]
	s_barrier
	s_setprio 1
.Lkmid_1441:
	ds_read_b128 v[132:135], v225 offset:32768
	ds_read_b128 v[136:139], v225 offset:33792
	ds_read_b128 v[140:143], v225 offset:34816
	ds_read_b128 v[144:147], v225 offset:35840
	ds_read_b128 v[148:151], v225 offset:49152
	ds_read_b128 v[152:155], v225 offset:50176
	ds_read_b128 v[156:159], v225 offset:51200
	ds_read_b128 v[160:163], v225 offset:52224
	s_add_u32 s52, s52, 0xb0000
	s_addc_u32 s53, s53, 0
	v_readfirstlane_b32 s31, v217
	v_lshl_add_u64 v[246:247], s[52:53], 0, v[184:185]
	s_mov_b32 m0, s31
	v_readfirstlane_b32 s31, v218
	ds_read_b128 v[164:167], v226 offset:32768
	ds_read_b128 v[168:171], v226 offset:33792
	ds_read_b128 v[172:175], v226 offset:34816
	ds_read_b128 v[176:179], v226 offset:35840
	ds_read_b128 v[180:183], v226 offset:36864
	ds_read_b128 v[228:231], v226 offset:37888
	ds_read_b128 v[232:235], v226 offset:38912
	ds_read_b128 v[236:239], v226 offset:39936
	global_load_lds_dwordx4 v[246:247], off
	v_lshl_add_u64 v[246:247], s[52:53], 0, v[186:187]
	s_mov_b32 m0, s31
	s_nop 0
	global_load_lds_dwordx4 v[246:247], off
	s_waitcnt vmcnt(8)
	s_waitcnt lgkmcnt(0)
	s_barrier
; #define WAIT_V(n) asm volatile("s_waitcnt vmcnt(" #n ")" ::: "memory")
; #define WAIT_L(n) asm volatile("s_waitcnt lgkmcnt(" #n ")" ::: "memory")
; #define BAR __builtin_amdgcn_s_barrier()
; #define SCHED __builtin_amdgcn_sched_barrier(0)
; #define STG_A(b, h, ptr) do { const char* _g = (ptr) + (h) * ahalf; LAS unsigned char* _l = lw + ((b) * 2 + (h)) * 16384; GLDS(_g + voa0, _l); GLDS(_g + voa1, _l + 8192); } while (0)
; #define STG_B(b, h, ptr) do { const char* _g = (ptr) + (h) * bhalf; LAS unsigned char* _l = lw + 65536 + ((b) * 2 + (h)) * 16384; GLDS(_g + vob0, _l); GLDS(_g + vob1, _l + 8192); } while (0)
; #define LDA(dst, b, h) _Pragma("unroll") for (int m = 0; m < 4; ++m) _Pragma("unroll") for (int k = 0; k < 2; ++k) dst[m][k] = *(const LAS bf16x8*)(la + ((b) * 2 + (h)) * 16384 + m * 2048 + k * 1024)
; #define MMA(ai, bj, Af, Bf) do { __builtin_amdgcn_s_setprio(1); \
;     _Pragma("unroll") for (int m = 0; m < 4; ++m) _Pragma("unroll") for (int n = 0; n < 2; ++n) _Pragma("unroll") for (int k = 0; k < 2; ++k) \
;         acc[ai][bj][m][n] = __builtin_amdgcn_mfma_f32_16x16x32_bf16(Bf[n][k], Af[m][k], acc[ai][bj][m][n], 0, 0, 0); \
;     __builtin_amdgcn_s_setprio(0); } while (0)
; template <int BMODE, class Epi, class TileFn>
; DEV void gemm_loop(LAS unsigned char* lds, const bf16_t* __restrict__ A, int lda, const bf16_t* __restrict__ B, int ldb, int K, const Epi& epi, int t0, int tstep, int tend, const TileFn& tf) {
;     ...
;             WAIT_V(8); WAIT_L(0); BAR; MMA(0, 0, At, B0); MMA(0, 1, At, B1); BAR; SCHED;
;             LDA(At, 1, 1); STG_B(1, 0, b3); STG_B(1, 1, b3); STG_A(1, 0, a3);
;             WAIT_V(8); WAIT_L(0); BAR; MMA(1, 0, At, B0); MMA(1, 1, At, B1); BAR; SCHED;
;         }
	s_setprio 0
	v_mfma_f32_16x16x32_bf16 v[128:131], v[132:135], v[164:167], v[128:131]
	v_mfma_f32_16x16x32_bf16 v[124:127], v[140:143], v[164:167], v[124:127]
	v_mfma_f32_16x16x32_bf16 v[108:111], v[132:135], v[172:175], v[108:111]
	v_mfma_f32_16x16x32_bf16 v[104:107], v[140:143], v[172:175], v[104:107]
	v_mfma_f32_16x16x32_bf16 v[92:95], v[132:135], v[180:183], v[92:95]
	v_mfma_f32_16x16x32_bf16 v[88:91], v[140:143], v[180:183], v[88:91]
	v_mfma_f32_16x16x32_bf16 v[76:79], v[132:135], v[232:235], v[76:79]
	v_mfma_f32_16x16x32_bf16 v[72:75], v[140:143], v[232:235], v[72:75]
	v_mfma_f32_16x16x32_bf16 v[128:131], v[136:139], v[168:171], v[128:131]
	v_mfma_f32_16x16x32_bf16 v[124:127], v[144:147], v[168:171], v[124:127]
	v_mfma_f32_16x16x32_bf16 v[108:111], v[136:139], v[176:179], v[108:111]
	v_mfma_f32_16x16x32_bf16 v[104:107], v[144:147], v[176:179], v[104:107]
	v_mfma_f32_16x16x32_bf16 v[92:95], v[136:139], v[228:231], v[92:95]
	v_mfma_f32_16x16x32_bf16 v[88:91], v[144:147], v[228:231], v[88:91]
	v_mfma_f32_16x16x32_bf16 v[76:79], v[136:139], v[236:239], v[76:79]
	v_mfma_f32_16x16x32_bf16 v[72:75], v[144:147], v[236:239], v[72:75]
	v_mfma_f32_16x16x32_bf16 v[116:119], v[148:151], v[164:167], v[116:119]
	v_mfma_f32_16x16x32_bf16 v[112:115], v[156:159], v[164:167], v[112:115]
	v_mfma_f32_16x16x32_bf16 v[100:103], v[148:151], v[172:175], v[100:103]
	v_mfma_f32_16x16x32_bf16 v[96:99], v[156:159], v[172:175], v[96:99]
	v_mfma_f32_16x16x32_bf16 v[84:87], v[148:151], v[180:183], v[84:87]
	v_mfma_f32_16x16x32_bf16 v[80:83], v[156:159], v[180:183], v[80:83]
	v_mfma_f32_16x16x32_bf16 v[68:71], v[148:151], v[232:235], v[68:71]
	v_mfma_f32_16x16x32_bf16 v[64:67], v[156:159], v[232:235], v[64:67]
	v_mfma_f32_16x16x32_bf16 v[116:119], v[152:155], v[168:171], v[116:119]
	v_mfma_f32_16x16x32_bf16 v[112:115], v[160:163], v[168:171], v[112:115]
	v_mfma_f32_16x16x32_bf16 v[100:103], v[152:155], v[176:179], v[100:103]
	v_mfma_f32_16x16x32_bf16 v[96:99], v[160:163], v[176:179], v[96:99]
	v_mfma_f32_16x16x32_bf16 v[84:87], v[152:155], v[228:231], v[84:87]
	v_mfma_f32_16x16x32_bf16 v[80:83], v[160:163], v[228:231], v[80:83]
	v_mfma_f32_16x16x32_bf16 v[68:71], v[152:155], v[236:239], v[68:71]
	v_mfma_f32_16x16x32_bf16 v[64:67], v[160:163], v[236:239], v[64:67]
	s_barrier
	s_setprio 1
	v_readfirstlane_b32 s31, v219
	v_lshl_add_u64 v[204:205], v[204:205], 0, s[2:3]
	s_mov_b32 m0, s31
	v_readfirstlane_b32 s31, v220
	s_add_u32 s8, s8, 0xb0080
	ds_read_b128 v[164:167], v226 offset:49152
	ds_read_b128 v[168:171], v226 offset:50176
	ds_read_b128 v[172:175], v226 offset:51200
	ds_read_b128 v[176:179], v226 offset:52224
	ds_read_b128 v[180:183], v226 offset:53248
	ds_read_b128 v[228:231], v226 offset:54272
	ds_read_b128 v[232:235], v226 offset:55296
	ds_read_b128 v[236:239], v226 offset:56320
	global_load_lds_dwordx4 v[204:205], off
	v_lshl_add_u64 v[204:205], v[240:241], 0, s[2:3]
	s_mov_b32 m0, s31
	s_addc_u32 s9, s9, 0
	v_readfirstlane_b32 s31, v223
	global_load_lds_dwordx4 v[204:205], off
	v_lshl_add_u64 v[204:205], s[8:9], 0, v[196:197]
	s_mov_b32 m0, s31
	s_nop 0
	global_load_lds_dwordx4 v[204:205], off
	v_lshl_add_u64 v[204:205], s[8:9], 0, v[198:199]
	v_readfirstlane_b32 s8, v224
	s_mov_b32 m0, s8
	v_readfirstlane_b32 s8, v221
	global_load_lds_dwordx4 v[204:205], off
	v_lshl_add_u64 v[204:205], v[242:243], 0, s[2:3]
	s_mov_b32 m0, s8
	v_readfirstlane_b32 s8, v222
	global_load_lds_dwordx4 v[204:205], off
	v_lshl_add_u64 v[204:205], v[244:245], 0, s[2:3]
	s_mov_b32 m0, s8
	s_nop 0
	global_load_lds_dwordx4 v[204:205], off
	s_waitcnt vmcnt(8)
	s_waitcnt lgkmcnt(0)
	s_barrier
	s_setprio 0
	v_mfma_f32_16x16x32_bf16 v[60:63], v[132:135], v[164:167], v[60:63]
	v_mfma_f32_16x16x32_bf16 v[56:59], v[140:143], v[164:167], v[56:59]
	v_mfma_f32_16x16x32_bf16 v[44:47], v[132:135], v[172:175], v[44:47]
	v_mfma_f32_16x16x32_bf16 v[40:43], v[140:143], v[172:175], v[40:43]
	v_mfma_f32_16x16x32_bf16 v[28:31], v[132:135], v[180:183], v[28:31]
	v_mfma_f32_16x16x32_bf16 v[24:27], v[140:143], v[180:183], v[24:27]
	v_mfma_f32_16x16x32_bf16 v[12:15], v[132:135], v[232:235], v[12:15]
	v_mfma_f32_16x16x32_bf16 v[8:11], v[140:143], v[232:235], v[8:11]
	v_mfma_f32_16x16x32_bf16 v[60:63], v[136:139], v[168:171], v[60:63]
	v_mfma_f32_16x16x32_bf16 v[56:59], v[144:147], v[168:171], v[56:59]
	v_mfma_f32_16x16x32_bf16 v[44:47], v[136:139], v[176:179], v[44:47]
	v_mfma_f32_16x16x32_bf16 v[40:43], v[144:147], v[176:179], v[40:43]
	v_mfma_f32_16x16x32_bf16 v[28:31], v[136:139], v[228:231], v[28:31]
	v_mfma_f32_16x16x32_bf16 v[24:27], v[144:147], v[228:231], v[24:27]
	v_mfma_f32_16x16x32_bf16 v[12:15], v[136:139], v[236:239], v[12:15]
	v_mfma_f32_16x16x32_bf16 v[8:11], v[144:147], v[236:239], v[8:11]
	v_mfma_f32_16x16x32_bf16 v[52:55], v[148:151], v[164:167], v[52:55]
	v_mfma_f32_16x16x32_bf16 v[48:51], v[156:159], v[164:167], v[48:51]
	v_mfma_f32_16x16x32_bf16 v[36:39], v[148:151], v[172:175], v[36:39]
	v_mfma_f32_16x16x32_bf16 v[32:35], v[156:159], v[172:175], v[32:35]
	v_mfma_f32_16x16x32_bf16 v[20:23], v[148:151], v[180:183], v[20:23]
	v_mfma_f32_16x16x32_bf16 v[16:19], v[156:159], v[180:183], v[16:19]
	v_mfma_f32_16x16x32_bf16 v[4:7], v[148:151], v[232:235], v[4:7]
	v_mfma_f32_16x16x32_bf16 v[0:3], v[156:159], v[232:235], v[0:3]
	v_mfma_f32_16x16x32_bf16 v[52:55], v[152:155], v[168:171], v[52:55]
	v_mfma_f32_16x16x32_bf16 v[48:51], v[160:163], v[168:171], v[48:51]
	v_mfma_f32_16x16x32_bf16 v[36:39], v[152:155], v[176:179], v[36:39]
	v_mfma_f32_16x16x32_bf16 v[32:35], v[160:163], v[176:179], v[32:35]
	v_mfma_f32_16x16x32_bf16 v[20:23], v[152:155], v[228:231], v[20:23]
	v_mfma_f32_16x16x32_bf16 v[16:19], v[160:163], v[228:231], v[16:19]
	v_mfma_f32_16x16x32_bf16 v[4:7], v[152:155], v[236:239], v[4:7]
	v_mfma_f32_16x16x32_bf16 v[0:3], v[160:163], v[236:239], v[0:3]
	s_barrier
	s_setprio 1
	s_add_i32 s77, s77, 2
	s_add_u32 s0, s0, 0x100
	s_addc_u32 s1, s1, 0
	s_cmp_gt_u32 s77, 41
	s_cbranch_scc0 .LBB0_1441
	s_setprio 0
	s_and_saveexec_b64 s[0:1], s[40:41]
	s_cbranch_execz .LBB0_1444
	s_barrier
